# 8-phase GEMM loops: phase-5 B-fragment LDS reads issued one phase earlier (balances reads per barrier interval)
# baseline (speedup 1.0000x reference)
.LBB0_254:
	s_add_u32 s10, s8, 0xfffc0080
	s_addc_u32 s11, s9, -1
	s_add_i32 s22, 0, 0x10000
	v_add_u32_e32 v92, s22, v191
	ds_read_b128 v[68:71], v92
	ds_read_b128 v[72:75], v92 offset:1024
	ds_read_b128 v[88:91], v92 offset:2048
	ds_read_b128 v[92:95], v92 offset:3072
	s_cmp_eq_u32 s15, 12
	s_cselect_b32 s13, s19, s11
	s_cselect_b32 s12, s18, s10
	s_cselect_b32 s11, s21, s14
	s_cselect_b32 s10, s20, s2
	v_lshl_add_u64 v[186:187], s[8:9], 0, v[166:167]
	s_add_i32 m0, s34, 0xc000
	ds_read_b128 v[112:115], v192
	ds_read_b128 v[116:119], v192 offset:1024
	ds_read_b128 v[152:155], v192 offset:2048
	ds_read_b128 v[156:159], v192 offset:3072
	ds_read_b128 v[170:173], v192 offset:4096
	ds_read_b128 v[174:177], v192 offset:5120
	ds_read_b128 v[178:181], v192 offset:6144
	ds_read_b128 v[182:185], v192 offset:7168
	global_load_lds_dwordx4 v[186:187], off
	v_lshl_add_u64 v[186:187], s[8:9], 0, v[168:169]
	s_add_i32 m0, s34, 0xe000
	s_nop 0
	global_load_lds_dwordx4 v[186:187], off
	s_waitcnt lgkmcnt(8)
	s_barrier
	s_waitcnt lgkmcnt(0)
	s_setprio 1
	s_waitcnt lgkmcnt(0)
	v_mfma_f32_16x16x32_bf16 v[148:151], v[68:71], v[112:115], v[148:151]
	v_mfma_f32_16x16x32_bf16 v[144:147], v[88:91], v[112:115], v[144:147]
	v_mfma_f32_16x16x32_bf16 v[132:135], v[68:71], v[152:155], v[132:135]
	v_mfma_f32_16x16x32_bf16 v[128:131], v[88:91], v[152:155], v[128:131]
	v_mfma_f32_16x16x32_bf16 v[108:111], v[68:71], v[170:173], v[108:111]
	v_mfma_f32_16x16x32_bf16 v[104:107], v[88:91], v[170:173], v[104:107]
	v_mfma_f32_16x16x32_bf16 v[84:87], v[68:71], v[178:181], v[84:87]
	v_mfma_f32_16x16x32_bf16 v[80:83], v[88:91], v[178:181], v[80:83]
	v_mfma_f32_16x16x32_bf16 v[148:151], v[72:75], v[116:119], v[148:151]
	v_mfma_f32_16x16x32_bf16 v[144:147], v[92:95], v[116:119], v[144:147]
	v_mfma_f32_16x16x32_bf16 v[132:135], v[72:75], v[156:159], v[132:135]
	v_mfma_f32_16x16x32_bf16 v[128:131], v[92:95], v[156:159], v[128:131]
	v_mfma_f32_16x16x32_bf16 v[108:111], v[72:75], v[174:177], v[108:111]
	v_mfma_f32_16x16x32_bf16 v[104:107], v[92:95], v[174:177], v[104:107]
	v_mfma_f32_16x16x32_bf16 v[84:87], v[72:75], v[182:185], v[84:87]
	v_mfma_f32_16x16x32_bf16 v[80:83], v[92:95], v[182:185], v[80:83]
	s_setprio 0
	s_barrier
	s_add_i32 s24, 0, 0x14000
	s_add_i32 s22, s22, s31
	v_add_u32_e32 v193, s24, v191
	v_lshl_add_u64 v[216:217], s[10:11], 0, v[160:161]
	s_mov_b32 m0, s22
	ds_read_b128 v[186:189], v193
	ds_read_b128 v[204:207], v193 offset:1024
	ds_read_b128 v[208:211], v193 offset:2048
	ds_read_b128 v[212:215], v193 offset:3072
	global_load_lds_dwordx4 v[216:217], off
	v_lshl_add_u64 v[236:237], s[10:11], 0, v[162:163]
	s_add_i32 m0, s22, 0x2000
	s_nop 0
	global_load_lds_dwordx4 v[236:237], off
	s_barrier
	s_waitcnt lgkmcnt(0)
	s_setprio 1
	s_waitcnt lgkmcnt(0)
	v_mfma_f32_16x16x32_bf16 v[140:143], v[186:189], v[112:115], v[140:143]
	v_mfma_f32_16x16x32_bf16 v[112:115], v[208:211], v[112:115], v[136:139]
	v_mfma_f32_16x16x32_bf16 v[120:123], v[208:211], v[152:155], v[120:123]
	v_mfma_f32_16x16x32_bf16 v[100:103], v[186:189], v[170:173], v[100:103]
	v_mfma_f32_16x16x32_bf16 v[96:99], v[208:211], v[170:173], v[96:99]
	v_mfma_f32_16x16x32_bf16 v[76:79], v[186:189], v[178:181], v[76:79]
	v_mfma_f32_16x16x32_bf16 v[64:67], v[208:211], v[178:181], v[64:67]
	v_mfma_f32_16x16x32_bf16 v[140:143], v[204:207], v[116:119], v[140:143]
	v_mfma_f32_16x16x32_bf16 v[112:115], v[212:215], v[116:119], v[112:115]
	v_mfma_f32_16x16x32_bf16 v[116:119], v[186:189], v[152:155], v[124:127]
	v_mfma_f32_16x16x32_bf16 v[120:123], v[212:215], v[156:159], v[120:123]
	v_mfma_f32_16x16x32_bf16 v[100:103], v[204:207], v[174:177], v[100:103]
	v_mfma_f32_16x16x32_bf16 v[96:99], v[212:215], v[174:177], v[96:99]
	v_mfma_f32_16x16x32_bf16 v[76:79], v[204:207], v[182:185], v[76:79]
	v_mfma_f32_16x16x32_bf16 v[64:67], v[212:215], v[182:185], v[64:67]
	v_mfma_f32_16x16x32_bf16 v[116:119], v[204:207], v[156:159], v[116:119]
	s_setprio 0
	s_mov_b32 m0, s34
	v_lshl_add_u64 v[238:239], s[12:13], 0, v[160:161]
	s_barrier
	ds_read_b128 v[124:127], v192 offset:16384
	ds_read_b128 v[136:139], v192 offset:17408
	ds_read_b128 v[152:155], v192 offset:18432
	ds_read_b128 v[156:159], v192 offset:19456
	ds_read_b128 v[170:173], v192 offset:20480
	ds_read_b128 v[174:177], v192 offset:21504
	ds_read_b128 v[178:181], v192 offset:22528
	ds_read_b128 v[182:185], v192 offset:23552
	global_load_lds_dwordx4 v[238:239], off
	v_lshl_add_u64 v[240:241], s[12:13], 0, v[162:163]
	s_mov_b32 m0, s36
	s_nop 0
	global_load_lds_dwordx4 v[240:241], off
	s_barrier
	s_waitcnt lgkmcnt(0)
	s_setprio 1
	s_waitcnt lgkmcnt(0)
	v_mfma_f32_16x16x32_bf16 v[60:63], v[68:71], v[124:127], v[60:63]
	v_mfma_f32_16x16x32_bf16 v[56:59], v[88:91], v[124:127], v[56:59]
	v_mfma_f32_16x16x32_bf16 v[44:47], v[68:71], v[152:155], v[44:47]
	v_mfma_f32_16x16x32_bf16 v[40:43], v[88:91], v[152:155], v[40:43]
	v_mfma_f32_16x16x32_bf16 v[28:31], v[68:71], v[170:173], v[28:31]
	v_mfma_f32_16x16x32_bf16 v[24:27], v[88:91], v[170:173], v[24:27]
	v_mfma_f32_16x16x32_bf16 v[12:15], v[68:71], v[178:181], v[12:15]
	v_mfma_f32_16x16x32_bf16 v[8:11], v[88:91], v[178:181], v[8:11]
	v_mfma_f32_16x16x32_bf16 v[60:63], v[72:75], v[136:139], v[60:63]
	v_mfma_f32_16x16x32_bf16 v[56:59], v[92:95], v[136:139], v[56:59]
	v_mfma_f32_16x16x32_bf16 v[44:47], v[72:75], v[156:159], v[44:47]
	v_mfma_f32_16x16x32_bf16 v[40:43], v[92:95], v[156:159], v[40:43]
	v_mfma_f32_16x16x32_bf16 v[28:31], v[72:75], v[174:177], v[28:31]
	v_mfma_f32_16x16x32_bf16 v[24:27], v[92:95], v[174:177], v[24:27]
	v_mfma_f32_16x16x32_bf16 v[12:15], v[72:75], v[182:185], v[12:15]
	v_mfma_f32_16x16x32_bf16 v[8:11], v[92:95], v[182:185], v[8:11]
	s_setprio 0
	s_barrier
	s_add_u32 s22, s10, 0x40000
	s_addc_u32 s23, s11, 0
	s_add_i32 s24, s24, s31
	v_lshl_add_u64 v[68:69], s[22:23], 0, v[160:161]
	s_mov_b32 m0, s24
	s_nop 0
	global_load_lds_dwordx4 v[68:69], off
	v_lshl_add_u64 v[68:69], s[22:23], 0, v[162:163]
	s_add_i32 m0, s24, 0x2000
	s_nop 0
	global_load_lds_dwordx4 v[68:69], off
	s_add_i32 s22, 0, 0x18000
	v_add_u32_e32 v92, s22, v191
	ds_read_b128 v[68:71], v92
	ds_read_b128 v[72:75], v92 offset:1024
	ds_read_b128 v[88:91], v92 offset:2048
	ds_read_b128 v[92:95], v92 offset:3072
	s_waitcnt vmcnt(6)
	s_barrier
	s_setprio 1
	v_mfma_f32_16x16x32_bf16 v[52:55], v[186:189], v[124:127], v[52:55]
	v_mfma_f32_16x16x32_bf16 v[48:51], v[208:211], v[124:127], v[48:51]
	v_mfma_f32_16x16x32_bf16 v[36:39], v[186:189], v[152:155], v[36:39]
	v_mfma_f32_16x16x32_bf16 v[32:35], v[208:211], v[152:155], v[32:35]
	v_mfma_f32_16x16x32_bf16 v[20:23], v[186:189], v[170:173], v[20:23]
	v_mfma_f32_16x16x32_bf16 v[16:19], v[208:211], v[170:173], v[16:19]
	v_mfma_f32_16x16x32_bf16 v[4:7], v[186:189], v[178:181], v[4:7]
	v_mfma_f32_16x16x32_bf16 v[0:3], v[208:211], v[178:181], v[0:3]
	v_mfma_f32_16x16x32_bf16 v[52:55], v[204:207], v[136:139], v[52:55]
	v_mfma_f32_16x16x32_bf16 v[48:51], v[212:215], v[136:139], v[48:51]
	v_mfma_f32_16x16x32_bf16 v[36:39], v[204:207], v[156:159], v[36:39]
	v_mfma_f32_16x16x32_bf16 v[32:35], v[212:215], v[156:159], v[32:35]
	v_mfma_f32_16x16x32_bf16 v[20:23], v[204:207], v[174:177], v[20:23]
	v_mfma_f32_16x16x32_bf16 v[16:19], v[212:215], v[174:177], v[16:19]
	v_mfma_f32_16x16x32_bf16 v[4:7], v[204:207], v[182:185], v[4:7]
	v_mfma_f32_16x16x32_bf16 v[0:3], v[212:215], v[182:185], v[0:3]
	s_setprio 0
	s_barrier
	s_add_u32 s12, s12, 0x40000
	s_addc_u32 s13, s13, 0
	s_mov_b32 m0, s37
	v_lshl_add_u64 v[186:187], s[12:13], 0, v[160:161]
	ds_read_b128 v[124:127], v192 offset:32768
	ds_read_b128 v[136:139], v192 offset:33792
	ds_read_b128 v[152:155], v192 offset:34816
	ds_read_b128 v[156:159], v192 offset:35840
	ds_read_b128 v[170:173], v192 offset:36864
	ds_read_b128 v[174:177], v192 offset:37888
	ds_read_b128 v[178:181], v192 offset:38912
	ds_read_b128 v[182:185], v192 offset:39936
	global_load_lds_dwordx4 v[186:187], off
	v_lshl_add_u64 v[186:187], s[12:13], 0, v[162:163]
	s_mov_b32 m0, s38
	s_nop 0
	global_load_lds_dwordx4 v[186:187], off
	s_waitcnt lgkmcnt(8)
	s_barrier
	s_waitcnt lgkmcnt(0)
	s_setprio 1
	s_waitcnt lgkmcnt(0)
	v_mfma_f32_16x16x32_bf16 v[148:151], v[68:71], v[124:127], v[148:151]
	v_mfma_f32_16x16x32_bf16 v[144:147], v[88:91], v[124:127], v[144:147]
	v_mfma_f32_16x16x32_bf16 v[132:135], v[68:71], v[152:155], v[132:135]
	v_mfma_f32_16x16x32_bf16 v[128:131], v[88:91], v[152:155], v[128:131]
	v_mfma_f32_16x16x32_bf16 v[108:111], v[68:71], v[170:173], v[108:111]
	v_mfma_f32_16x16x32_bf16 v[104:107], v[88:91], v[170:173], v[104:107]
	v_mfma_f32_16x16x32_bf16 v[84:87], v[68:71], v[178:181], v[84:87]
	v_mfma_f32_16x16x32_bf16 v[80:83], v[88:91], v[178:181], v[80:83]
	v_mfma_f32_16x16x32_bf16 v[148:151], v[72:75], v[136:139], v[148:151]
	v_mfma_f32_16x16x32_bf16 v[144:147], v[92:95], v[136:139], v[144:147]
	v_mfma_f32_16x16x32_bf16 v[132:135], v[72:75], v[156:159], v[132:135]
	v_mfma_f32_16x16x32_bf16 v[128:131], v[92:95], v[156:159], v[128:131]
	v_mfma_f32_16x16x32_bf16 v[108:111], v[72:75], v[174:177], v[108:111]
	v_mfma_f32_16x16x32_bf16 v[104:107], v[92:95], v[174:177], v[104:107]
	v_mfma_f32_16x16x32_bf16 v[84:87], v[72:75], v[182:185], v[84:87]
	v_mfma_f32_16x16x32_bf16 v[80:83], v[92:95], v[182:185], v[80:83]
	s_setprio 0
	s_barrier
	s_add_i32 s12, 0, 0x1c000
	s_add_i32 s13, s22, s31
	v_add_u32_e32 v193, s12, v191
	v_lshl_add_u64 v[216:217], v[216:217], 0, s[82:83]
	s_mov_b32 m0, s13
	ds_read_b128 v[186:189], v193
	ds_read_b128 v[204:207], v193 offset:1024
	ds_read_b128 v[208:211], v193 offset:2048
	ds_read_b128 v[212:215], v193 offset:3072
	global_load_lds_dwordx4 v[216:217], off
	v_lshl_add_u64 v[216:217], v[236:237], 0, s[82:83]
	s_add_i32 m0, s13, 0x2000
	s_nop 0
	global_load_lds_dwordx4 v[216:217], off
	s_barrier
	s_waitcnt lgkmcnt(0)
	s_setprio 1
	s_waitcnt lgkmcnt(0)
	v_mfma_f32_16x16x32_bf16 v[140:143], v[186:189], v[124:127], v[140:143]
	v_mfma_f32_16x16x32_bf16 v[112:115], v[208:211], v[124:127], v[112:115]
	v_mfma_f32_16x16x32_bf16 v[140:143], v[204:207], v[136:139], v[140:143]
	v_mfma_f32_16x16x32_bf16 v[136:139], v[212:215], v[136:139], v[112:115]
	v_mfma_f32_16x16x32_bf16 v[112:115], v[186:189], v[152:155], v[116:119]
	v_mfma_f32_16x16x32_bf16 v[124:127], v[204:207], v[156:159], v[112:115]
	v_mfma_f32_16x16x32_bf16 v[112:115], v[208:211], v[152:155], v[120:123]
	v_mfma_f32_16x16x32_bf16 v[100:103], v[186:189], v[170:173], v[100:103]
	v_mfma_f32_16x16x32_bf16 v[96:99], v[208:211], v[170:173], v[96:99]
	v_mfma_f32_16x16x32_bf16 v[76:79], v[186:189], v[178:181], v[76:79]
	v_mfma_f32_16x16x32_bf16 v[64:67], v[208:211], v[178:181], v[64:67]
	v_mfma_f32_16x16x32_bf16 v[120:123], v[212:215], v[156:159], v[112:115]
	v_mfma_f32_16x16x32_bf16 v[100:103], v[204:207], v[174:177], v[100:103]
	v_mfma_f32_16x16x32_bf16 v[96:99], v[212:215], v[174:177], v[96:99]
	v_mfma_f32_16x16x32_bf16 v[76:79], v[204:207], v[182:185], v[76:79]
	v_mfma_f32_16x16x32_bf16 v[64:67], v[212:215], v[182:185], v[64:67]
	s_setprio 0
	s_mov_b32 m0, s40
	v_lshl_add_u64 v[216:217], v[238:239], 0, s[82:83]
	s_barrier
	ds_read_b128 v[112:115], v192 offset:49152
	ds_read_b128 v[116:119], v192 offset:50176
	ds_read_b128 v[152:155], v192 offset:51200
	ds_read_b128 v[156:159], v192 offset:52224
	ds_read_b128 v[170:173], v192 offset:53248
	ds_read_b128 v[174:177], v192 offset:54272
	ds_read_b128 v[178:181], v192 offset:55296
	ds_read_b128 v[182:185], v192 offset:56320
	global_load_lds_dwordx4 v[216:217], off
	v_lshl_add_u64 v[216:217], v[240:241], 0, s[82:83]
	s_mov_b32 m0, s41
	s_nop 0
	global_load_lds_dwordx4 v[216:217], off
	s_barrier
	s_waitcnt lgkmcnt(0)
	s_setprio 1
	s_waitcnt lgkmcnt(0)
	v_mfma_f32_16x16x32_bf16 v[60:63], v[68:71], v[112:115], v[60:63]
	v_mfma_f32_16x16x32_bf16 v[56:59], v[88:91], v[112:115], v[56:59]
	v_mfma_f32_16x16x32_bf16 v[44:47], v[68:71], v[152:155], v[44:47]
	v_mfma_f32_16x16x32_bf16 v[40:43], v[88:91], v[152:155], v[40:43]
	v_mfma_f32_16x16x32_bf16 v[28:31], v[68:71], v[170:173], v[28:31]
	v_mfma_f32_16x16x32_bf16 v[24:27], v[88:91], v[170:173], v[24:27]
	v_mfma_f32_16x16x32_bf16 v[12:15], v[68:71], v[178:181], v[12:15]
	v_mfma_f32_16x16x32_bf16 v[8:11], v[88:91], v[178:181], v[8:11]
	v_mfma_f32_16x16x32_bf16 v[60:63], v[72:75], v[116:119], v[60:63]
	v_mfma_f32_16x16x32_bf16 v[56:59], v[92:95], v[116:119], v[56:59]
	v_mfma_f32_16x16x32_bf16 v[44:47], v[72:75], v[156:159], v[44:47]
	v_mfma_f32_16x16x32_bf16 v[40:43], v[92:95], v[156:159], v[40:43]
	v_mfma_f32_16x16x32_bf16 v[28:31], v[72:75], v[174:177], v[28:31]
	v_mfma_f32_16x16x32_bf16 v[24:27], v[92:95], v[174:177], v[24:27]
	v_mfma_f32_16x16x32_bf16 v[12:15], v[72:75], v[182:185], v[12:15]
	v_mfma_f32_16x16x32_bf16 v[8:11], v[92:95], v[182:185], v[8:11]
	s_setprio 0
	s_barrier
	s_add_u32 s10, s10, 0x40080
	s_addc_u32 s11, s11, 0
	s_add_i32 s12, s12, s31
	v_lshl_add_u64 v[68:69], s[10:11], 0, v[160:161]
	s_mov_b32 m0, s12
	s_nop 0
	global_load_lds_dwordx4 v[68:69], off
	v_lshl_add_u64 v[68:69], s[10:11], 0, v[162:163]
	s_add_i32 m0, s12, 0x2000
	s_nop 0
	global_load_lds_dwordx4 v[68:69], off
	s_waitcnt vmcnt(6)
	s_barrier
	s_setprio 1
	v_mfma_f32_16x16x32_bf16 v[52:55], v[186:189], v[112:115], v[52:55]
	v_mfma_f32_16x16x32_bf16 v[48:51], v[208:211], v[112:115], v[48:51]
	v_mfma_f32_16x16x32_bf16 v[36:39], v[186:189], v[152:155], v[36:39]
	v_mfma_f32_16x16x32_bf16 v[32:35], v[208:211], v[152:155], v[32:35]
	v_mfma_f32_16x16x32_bf16 v[20:23], v[186:189], v[170:173], v[20:23]
	v_mfma_f32_16x16x32_bf16 v[16:19], v[208:211], v[170:173], v[16:19]
	v_mfma_f32_16x16x32_bf16 v[4:7], v[186:189], v[178:181], v[4:7]
	v_mfma_f32_16x16x32_bf16 v[0:3], v[208:211], v[178:181], v[0:3]
	v_mfma_f32_16x16x32_bf16 v[52:55], v[204:207], v[116:119], v[52:55]
	v_mfma_f32_16x16x32_bf16 v[48:51], v[212:215], v[116:119], v[48:51]
	v_mfma_f32_16x16x32_bf16 v[36:39], v[204:207], v[156:159], v[36:39]
	v_mfma_f32_16x16x32_bf16 v[32:35], v[212:215], v[156:159], v[32:35]
	v_mfma_f32_16x16x32_bf16 v[20:23], v[204:207], v[174:177], v[20:23]
	v_mfma_f32_16x16x32_bf16 v[16:19], v[212:215], v[174:177], v[16:19]
	v_mfma_f32_16x16x32_bf16 v[4:7], v[204:207], v[182:185], v[4:7]
	v_mfma_f32_16x16x32_bf16 v[0:3], v[212:215], v[182:185], v[0:3]
	s_setprio 0
	s_add_i32 s15, s15, 2
	s_add_u32 s8, s8, 0x100
	s_addc_u32 s9, s9, 0
	s_add_u32 s2, s2, 0x100
	s_addc_u32 s14, s14, 0
	s_cmp_gt_u32 s15, 13
	s_barrier
	s_cbranch_scc0 .LBB0_254
	s_lshl_b32 s10, s3, 8
	s_cmp_lt_i32 s3, 2
	s_cbranch_scc1 .LBB0_273
	s_cmp_lt_u32 s3, 4
	s_cbranch_scc1 .LBB0_274
	s_cmp_lt_i32 s3, 6
	s_cbranch_scc1 .LBB0_275
	s_cmp_gt_u32 s3, 8
	s_mov_b64 s[14:15], -1
	s_cbranch_scc0 .LBB0_271
	s_cmp_gt_u32 s3, 11
	s_cbranch_scc0 .LBB0_268
	s_cmp_gt_u32 s3, 14
	s_cbranch_scc0 .LBB0_265
	s_cmp_gt_u32 s3, 17
	s_mov_b64 s[8:9], -1
	s_cbranch_scc0 .LBB0_263
	s_add_i32 s2, s10, 0xffffee00
	s_mov_b64 s[8:9], 0

.LBB0_604:
	s_add_u32 s12, s10, 0xfffc0080
	s_addc_u32 s13, s11, -1
	s_add_i32 s36, 0, 0x10000
	v_add_u32_e32 v139, s36, v137
	ds_read_b128 v[140:143], v139
	ds_read_b128 v[144:147], v139 offset:1024
	ds_read_b128 v[148:151], v139 offset:2048
	ds_read_b128 v[152:155], v139 offset:3072
	s_cmp_eq_u32 s35, 12
	s_cselect_b32 s15, s7, s13
	s_cselect_b32 s14, s6, s12
	s_cselect_b32 s13, s9, s34
	s_cselect_b32 s12, s8, s31
	v_lshl_add_u64 v[188:189], s[10:11], 0, v[132:133]
	s_add_i32 m0, s22, 0xc000
	ds_read_b128 v[156:159], v138
	ds_read_b128 v[160:163], v138 offset:1024
	ds_read_b128 v[164:167], v138 offset:2048
	ds_read_b128 v[168:171], v138 offset:3072
	ds_read_b128 v[172:175], v138 offset:4096
	ds_read_b128 v[176:179], v138 offset:5120
	ds_read_b128 v[180:183], v138 offset:6144
	ds_read_b128 v[184:187], v138 offset:7168
	global_load_lds_dwordx4 v[188:189], off
	v_lshl_add_u64 v[188:189], s[10:11], 0, v[134:135]
	s_add_i32 m0, s22, 0xe000
	s_nop 0
	global_load_lds_dwordx4 v[188:189], off
	s_waitcnt lgkmcnt(8)
	s_barrier
	s_waitcnt lgkmcnt(0)
	s_setprio 1
	s_waitcnt lgkmcnt(0)
	v_mfma_f32_16x16x32_bf16 v[124:127], v[140:143], v[156:159], v[124:127]
	v_mfma_f32_16x16x32_bf16 v[120:123], v[148:151], v[156:159], v[120:123]
	v_mfma_f32_16x16x32_bf16 v[108:111], v[140:143], v[164:167], v[108:111]
	v_mfma_f32_16x16x32_bf16 v[104:107], v[148:151], v[164:167], v[104:107]
	v_mfma_f32_16x16x32_bf16 v[92:95], v[140:143], v[172:175], v[92:95]
	v_mfma_f32_16x16x32_bf16 v[88:91], v[148:151], v[172:175], v[88:91]
	v_mfma_f32_16x16x32_bf16 v[76:79], v[140:143], v[180:183], v[76:79]
	v_mfma_f32_16x16x32_bf16 v[72:75], v[148:151], v[180:183], v[72:75]
	v_mfma_f32_16x16x32_bf16 v[124:127], v[144:147], v[160:163], v[124:127]
	v_mfma_f32_16x16x32_bf16 v[120:123], v[152:155], v[160:163], v[120:123]
	v_mfma_f32_16x16x32_bf16 v[108:111], v[144:147], v[168:171], v[108:111]
	v_mfma_f32_16x16x32_bf16 v[104:107], v[152:155], v[168:171], v[104:107]
	v_mfma_f32_16x16x32_bf16 v[92:95], v[144:147], v[176:179], v[92:95]
	v_mfma_f32_16x16x32_bf16 v[88:91], v[152:155], v[176:179], v[88:91]
	v_mfma_f32_16x16x32_bf16 v[76:79], v[144:147], v[184:187], v[76:79]
	v_mfma_f32_16x16x32_bf16 v[72:75], v[152:155], v[184:187], v[72:75]
	s_setprio 0
	s_barrier
	s_add_i32 s38, 0, 0x14000
	s_add_i32 s36, s36, s21
	v_add_u32_e32 v139, s38, v137
	v_lshl_add_u64 v[192:193], s[12:13], 0, v[130:131]
	s_mov_b32 m0, s36
	ds_read_b128 v[188:191], v139
	ds_read_b128 v[204:207], v139 offset:1024
	ds_read_b128 v[208:211], v139 offset:2048
	ds_read_b128 v[212:215], v139 offset:3072
	global_load_lds_dwordx4 v[192:193], off
	v_lshl_add_u64 v[216:217], s[12:13], 0, v[128:129]
	s_add_i32 m0, s36, 0x2000
	s_nop 0
	global_load_lds_dwordx4 v[216:217], off
	s_barrier
	s_waitcnt lgkmcnt(0)
	s_setprio 1
	s_waitcnt lgkmcnt(0)
	v_mfma_f32_16x16x32_bf16 v[116:119], v[188:191], v[156:159], v[116:119]
	v_mfma_f32_16x16x32_bf16 v[112:115], v[208:211], v[156:159], v[112:115]
	v_mfma_f32_16x16x32_bf16 v[100:103], v[188:191], v[164:167], v[100:103]
	v_mfma_f32_16x16x32_bf16 v[96:99], v[208:211], v[164:167], v[96:99]
	v_mfma_f32_16x16x32_bf16 v[84:87], v[188:191], v[172:175], v[84:87]
	v_mfma_f32_16x16x32_bf16 v[80:83], v[208:211], v[172:175], v[80:83]
	v_mfma_f32_16x16x32_bf16 v[68:71], v[188:191], v[180:183], v[68:71]
	v_mfma_f32_16x16x32_bf16 v[64:67], v[208:211], v[180:183], v[64:67]
	v_mfma_f32_16x16x32_bf16 v[116:119], v[204:207], v[160:163], v[116:119]
	v_mfma_f32_16x16x32_bf16 v[112:115], v[212:215], v[160:163], v[112:115]
	v_mfma_f32_16x16x32_bf16 v[100:103], v[204:207], v[168:171], v[100:103]
	v_mfma_f32_16x16x32_bf16 v[96:99], v[212:215], v[168:171], v[96:99]
	v_mfma_f32_16x16x32_bf16 v[84:87], v[204:207], v[176:179], v[84:87]
	v_mfma_f32_16x16x32_bf16 v[80:83], v[212:215], v[176:179], v[80:83]
	v_mfma_f32_16x16x32_bf16 v[68:71], v[204:207], v[184:187], v[68:71]
	v_mfma_f32_16x16x32_bf16 v[64:67], v[212:215], v[184:187], v[64:67]
	s_setprio 0
	s_mov_b32 m0, s22
	v_lshl_add_u64 v[236:237], s[14:15], 0, v[130:131]
	s_barrier
	ds_read_b128 v[156:159], v138 offset:16384
	ds_read_b128 v[160:163], v138 offset:17408
	ds_read_b128 v[164:167], v138 offset:18432
	ds_read_b128 v[168:171], v138 offset:19456
	ds_read_b128 v[172:175], v138 offset:20480
	ds_read_b128 v[176:179], v138 offset:21504
	ds_read_b128 v[180:183], v138 offset:22528
	ds_read_b128 v[184:187], v138 offset:23552
	global_load_lds_dwordx4 v[236:237], off
	v_lshl_add_u64 v[238:239], s[14:15], 0, v[128:129]
	s_mov_b32 m0, s23
	s_nop 0
	global_load_lds_dwordx4 v[238:239], off
	s_barrier
	s_waitcnt lgkmcnt(0)
	s_setprio 1
	s_waitcnt lgkmcnt(0)
	v_mfma_f32_16x16x32_bf16 v[60:63], v[140:143], v[156:159], v[60:63]
	v_mfma_f32_16x16x32_bf16 v[56:59], v[148:151], v[156:159], v[56:59]
	v_mfma_f32_16x16x32_bf16 v[44:47], v[140:143], v[164:167], v[44:47]
	v_mfma_f32_16x16x32_bf16 v[40:43], v[148:151], v[164:167], v[40:43]
	v_mfma_f32_16x16x32_bf16 v[28:31], v[140:143], v[172:175], v[28:31]
	v_mfma_f32_16x16x32_bf16 v[24:27], v[148:151], v[172:175], v[24:27]
	v_mfma_f32_16x16x32_bf16 v[12:15], v[140:143], v[180:183], v[12:15]
	v_mfma_f32_16x16x32_bf16 v[8:11], v[148:151], v[180:183], v[8:11]
	v_mfma_f32_16x16x32_bf16 v[60:63], v[144:147], v[160:163], v[60:63]
	v_mfma_f32_16x16x32_bf16 v[56:59], v[152:155], v[160:163], v[56:59]
	v_mfma_f32_16x16x32_bf16 v[44:47], v[144:147], v[168:171], v[44:47]
	v_mfma_f32_16x16x32_bf16 v[40:43], v[152:155], v[168:171], v[40:43]
	v_mfma_f32_16x16x32_bf16 v[28:31], v[144:147], v[176:179], v[28:31]
	v_mfma_f32_16x16x32_bf16 v[24:27], v[152:155], v[176:179], v[24:27]
	v_mfma_f32_16x16x32_bf16 v[12:15], v[144:147], v[184:187], v[12:15]
	v_mfma_f32_16x16x32_bf16 v[8:11], v[152:155], v[184:187], v[8:11]
	s_setprio 0
	s_barrier
	s_add_u32 s36, s12, 0x40000
	s_addc_u32 s37, s13, 0
	s_add_i32 s38, s38, s21
	v_lshl_add_u64 v[140:141], s[36:37], 0, v[130:131]
	s_mov_b32 m0, s38
	s_nop 0
	global_load_lds_dwordx4 v[140:141], off
	v_lshl_add_u64 v[140:141], s[36:37], 0, v[128:129]
	s_add_i32 m0, s38, 0x2000
	s_nop 0
	global_load_lds_dwordx4 v[140:141], off
	s_add_i32 s36, 0, 0x18000
	v_add_u32_e32 v139, s36, v137
	ds_read_b128 v[140:143], v139
	ds_read_b128 v[144:147], v139 offset:1024
	ds_read_b128 v[148:151], v139 offset:2048
	ds_read_b128 v[152:155], v139 offset:3072
	s_waitcnt vmcnt(6)
	s_barrier
	s_setprio 1
	v_mfma_f32_16x16x32_bf16 v[52:55], v[188:191], v[156:159], v[52:55]
	v_mfma_f32_16x16x32_bf16 v[48:51], v[208:211], v[156:159], v[48:51]
	v_mfma_f32_16x16x32_bf16 v[36:39], v[188:191], v[164:167], v[36:39]
	v_mfma_f32_16x16x32_bf16 v[32:35], v[208:211], v[164:167], v[32:35]
	v_mfma_f32_16x16x32_bf16 v[20:23], v[188:191], v[172:175], v[20:23]
	v_mfma_f32_16x16x32_bf16 v[16:19], v[208:211], v[172:175], v[16:19]
	v_mfma_f32_16x16x32_bf16 v[4:7], v[188:191], v[180:183], v[4:7]
	v_mfma_f32_16x16x32_bf16 v[0:3], v[208:211], v[180:183], v[0:3]
	v_mfma_f32_16x16x32_bf16 v[52:55], v[204:207], v[160:163], v[52:55]
	v_mfma_f32_16x16x32_bf16 v[48:51], v[212:215], v[160:163], v[48:51]
	v_mfma_f32_16x16x32_bf16 v[36:39], v[204:207], v[168:171], v[36:39]
	v_mfma_f32_16x16x32_bf16 v[32:35], v[212:215], v[168:171], v[32:35]
	v_mfma_f32_16x16x32_bf16 v[20:23], v[204:207], v[176:179], v[20:23]
	v_mfma_f32_16x16x32_bf16 v[16:19], v[212:215], v[176:179], v[16:19]
	v_mfma_f32_16x16x32_bf16 v[4:7], v[204:207], v[184:187], v[4:7]
	v_mfma_f32_16x16x32_bf16 v[0:3], v[212:215], v[184:187], v[0:3]
	s_setprio 0
	s_barrier
	s_add_u32 s14, s14, 0x40000
	s_addc_u32 s15, s15, 0
	s_mov_b32 m0, s24
	v_lshl_add_u64 v[188:189], s[14:15], 0, v[130:131]
	ds_read_b128 v[156:159], v138 offset:32768
	ds_read_b128 v[160:163], v138 offset:33792
	ds_read_b128 v[164:167], v138 offset:34816
	ds_read_b128 v[168:171], v138 offset:35840
	ds_read_b128 v[172:175], v138 offset:36864
	ds_read_b128 v[176:179], v138 offset:37888
	ds_read_b128 v[180:183], v138 offset:38912
	ds_read_b128 v[184:187], v138 offset:39936
	global_load_lds_dwordx4 v[188:189], off
	v_lshl_add_u64 v[188:189], s[14:15], 0, v[128:129]
	s_mov_b32 m0, s25
	s_nop 0
	global_load_lds_dwordx4 v[188:189], off
	s_waitcnt lgkmcnt(8)
	s_barrier
	s_waitcnt lgkmcnt(0)
	s_setprio 1
	s_waitcnt lgkmcnt(0)
	v_mfma_f32_16x16x32_bf16 v[124:127], v[140:143], v[156:159], v[124:127]
	v_mfma_f32_16x16x32_bf16 v[120:123], v[148:151], v[156:159], v[120:123]
	v_mfma_f32_16x16x32_bf16 v[108:111], v[140:143], v[164:167], v[108:111]
	v_mfma_f32_16x16x32_bf16 v[104:107], v[148:151], v[164:167], v[104:107]
	v_mfma_f32_16x16x32_bf16 v[92:95], v[140:143], v[172:175], v[92:95]
	v_mfma_f32_16x16x32_bf16 v[88:91], v[148:151], v[172:175], v[88:91]
	v_mfma_f32_16x16x32_bf16 v[76:79], v[140:143], v[180:183], v[76:79]
	v_mfma_f32_16x16x32_bf16 v[72:75], v[148:151], v[180:183], v[72:75]
	v_mfma_f32_16x16x32_bf16 v[124:127], v[144:147], v[160:163], v[124:127]
	v_mfma_f32_16x16x32_bf16 v[120:123], v[152:155], v[160:163], v[120:123]
	v_mfma_f32_16x16x32_bf16 v[108:111], v[144:147], v[168:171], v[108:111]
	v_mfma_f32_16x16x32_bf16 v[104:107], v[152:155], v[168:171], v[104:107]
	v_mfma_f32_16x16x32_bf16 v[92:95], v[144:147], v[176:179], v[92:95]
	v_mfma_f32_16x16x32_bf16 v[88:91], v[152:155], v[176:179], v[88:91]
	v_mfma_f32_16x16x32_bf16 v[76:79], v[144:147], v[184:187], v[76:79]
	v_mfma_f32_16x16x32_bf16 v[72:75], v[152:155], v[184:187], v[72:75]
	s_setprio 0
	s_barrier
	s_add_i32 s14, 0, 0x1c000
	s_add_i32 s15, s36, s21
	v_add_u32_e32 v139, s14, v137
	v_lshl_add_u64 v[192:193], v[192:193], 0, s[82:83]
	s_mov_b32 m0, s15
	ds_read_b128 v[188:191], v139
	ds_read_b128 v[204:207], v139 offset:1024
	ds_read_b128 v[208:211], v139 offset:2048
	ds_read_b128 v[212:215], v139 offset:3072
	global_load_lds_dwordx4 v[192:193], off
	v_lshl_add_u64 v[192:193], v[216:217], 0, s[82:83]
	s_add_i32 m0, s15, 0x2000
	s_nop 0
	global_load_lds_dwordx4 v[192:193], off
	s_barrier
	s_waitcnt lgkmcnt(0)
	s_setprio 1
	s_waitcnt lgkmcnt(0)
	v_mfma_f32_16x16x32_bf16 v[116:119], v[188:191], v[156:159], v[116:119]
	v_mfma_f32_16x16x32_bf16 v[112:115], v[208:211], v[156:159], v[112:115]
	v_mfma_f32_16x16x32_bf16 v[100:103], v[188:191], v[164:167], v[100:103]
	v_mfma_f32_16x16x32_bf16 v[96:99], v[208:211], v[164:167], v[96:99]
	v_mfma_f32_16x16x32_bf16 v[84:87], v[188:191], v[172:175], v[84:87]
	v_mfma_f32_16x16x32_bf16 v[80:83], v[208:211], v[172:175], v[80:83]
	v_mfma_f32_16x16x32_bf16 v[68:71], v[188:191], v[180:183], v[68:71]
	v_mfma_f32_16x16x32_bf16 v[64:67], v[208:211], v[180:183], v[64:67]
	v_mfma_f32_16x16x32_bf16 v[116:119], v[204:207], v[160:163], v[116:119]
	v_mfma_f32_16x16x32_bf16 v[112:115], v[212:215], v[160:163], v[112:115]
	v_mfma_f32_16x16x32_bf16 v[100:103], v[204:207], v[168:171], v[100:103]
	v_mfma_f32_16x16x32_bf16 v[96:99], v[212:215], v[168:171], v[96:99]
	v_mfma_f32_16x16x32_bf16 v[84:87], v[204:207], v[176:179], v[84:87]
	v_mfma_f32_16x16x32_bf16 v[80:83], v[212:215], v[176:179], v[80:83]
	v_mfma_f32_16x16x32_bf16 v[68:71], v[204:207], v[184:187], v[68:71]
	v_mfma_f32_16x16x32_bf16 v[64:67], v[212:215], v[184:187], v[64:67]
	s_setprio 0
	s_mov_b32 m0, s26
	v_lshl_add_u64 v[192:193], v[236:237], 0, s[82:83]
	s_barrier
	ds_read_b128 v[156:159], v138 offset:49152
	ds_read_b128 v[160:163], v138 offset:50176
	ds_read_b128 v[164:167], v138 offset:51200
	ds_read_b128 v[168:171], v138 offset:52224
	ds_read_b128 v[172:175], v138 offset:53248
	ds_read_b128 v[176:179], v138 offset:54272
	ds_read_b128 v[180:183], v138 offset:55296
	ds_read_b128 v[184:187], v138 offset:56320
	global_load_lds_dwordx4 v[192:193], off
	v_lshl_add_u64 v[192:193], v[238:239], 0, s[82:83]
	s_mov_b32 m0, s27
	s_nop 0
	global_load_lds_dwordx4 v[192:193], off
	s_barrier
	s_waitcnt lgkmcnt(0)
	s_setprio 1
	s_waitcnt lgkmcnt(0)
	v_mfma_f32_16x16x32_bf16 v[60:63], v[140:143], v[156:159], v[60:63]
	v_mfma_f32_16x16x32_bf16 v[56:59], v[148:151], v[156:159], v[56:59]
	v_mfma_f32_16x16x32_bf16 v[44:47], v[140:143], v[164:167], v[44:47]
	v_mfma_f32_16x16x32_bf16 v[40:43], v[148:151], v[164:167], v[40:43]
	v_mfma_f32_16x16x32_bf16 v[28:31], v[140:143], v[172:175], v[28:31]
	v_mfma_f32_16x16x32_bf16 v[24:27], v[148:151], v[172:175], v[24:27]
	v_mfma_f32_16x16x32_bf16 v[12:15], v[140:143], v[180:183], v[12:15]
	v_mfma_f32_16x16x32_bf16 v[8:11], v[148:151], v[180:183], v[8:11]
	v_mfma_f32_16x16x32_bf16 v[60:63], v[144:147], v[160:163], v[60:63]
	v_mfma_f32_16x16x32_bf16 v[56:59], v[152:155], v[160:163], v[56:59]
	v_mfma_f32_16x16x32_bf16 v[44:47], v[144:147], v[168:171], v[44:47]
	v_mfma_f32_16x16x32_bf16 v[40:43], v[152:155], v[168:171], v[40:43]
	v_mfma_f32_16x16x32_bf16 v[28:31], v[144:147], v[176:179], v[28:31]
	v_mfma_f32_16x16x32_bf16 v[24:27], v[152:155], v[176:179], v[24:27]
	v_mfma_f32_16x16x32_bf16 v[12:15], v[144:147], v[184:187], v[12:15]
	v_mfma_f32_16x16x32_bf16 v[8:11], v[152:155], v[184:187], v[8:11]
	s_setprio 0
	s_barrier
	s_add_u32 s12, s12, 0x40080
	s_addc_u32 s13, s13, 0
	s_add_i32 s14, s14, s21
	v_lshl_add_u64 v[140:141], s[12:13], 0, v[130:131]
	s_mov_b32 m0, s14
	s_nop 0
	global_load_lds_dwordx4 v[140:141], off
	v_lshl_add_u64 v[140:141], s[12:13], 0, v[128:129]
	s_add_i32 m0, s14, 0x2000
	s_nop 0
	global_load_lds_dwordx4 v[140:141], off
	s_waitcnt vmcnt(6)
	s_barrier
	s_setprio 1
	v_mfma_f32_16x16x32_bf16 v[52:55], v[188:191], v[156:159], v[52:55]
	v_mfma_f32_16x16x32_bf16 v[48:51], v[208:211], v[156:159], v[48:51]
	v_mfma_f32_16x16x32_bf16 v[36:39], v[188:191], v[164:167], v[36:39]
	v_mfma_f32_16x16x32_bf16 v[32:35], v[208:211], v[164:167], v[32:35]
	v_mfma_f32_16x16x32_bf16 v[20:23], v[188:191], v[172:175], v[20:23]
	v_mfma_f32_16x16x32_bf16 v[16:19], v[208:211], v[172:175], v[16:19]
	v_mfma_f32_16x16x32_bf16 v[4:7], v[188:191], v[180:183], v[4:7]
	v_mfma_f32_16x16x32_bf16 v[0:3], v[208:211], v[180:183], v[0:3]
	v_mfma_f32_16x16x32_bf16 v[52:55], v[204:207], v[160:163], v[52:55]
	v_mfma_f32_16x16x32_bf16 v[48:51], v[212:215], v[160:163], v[48:51]
	v_mfma_f32_16x16x32_bf16 v[36:39], v[204:207], v[168:171], v[36:39]
	v_mfma_f32_16x16x32_bf16 v[32:35], v[212:215], v[168:171], v[32:35]
	v_mfma_f32_16x16x32_bf16 v[20:23], v[204:207], v[176:179], v[20:23]
	v_mfma_f32_16x16x32_bf16 v[16:19], v[212:215], v[176:179], v[16:19]
	v_mfma_f32_16x16x32_bf16 v[4:7], v[204:207], v[184:187], v[4:7]
	v_mfma_f32_16x16x32_bf16 v[0:3], v[212:215], v[184:187], v[0:3]
	s_setprio 0
	s_add_i32 s35, s35, 2
	s_add_u32 s10, s10, 0x100
	s_addc_u32 s11, s11, 0
	s_add_u32 s31, s31, 0x100
	s_addc_u32 s34, s34, 0
	s_cmp_gt_u32 s35, 13
	s_barrier
	s_cbranch_scc0 .LBB0_604
	v_exp_f32_e32 v124, v124
	v_exp_f32_e32 v125, v125
	v_exp_f32_e32 v120, v120
	v_exp_f32_e32 v121, v121
	v_add_f32_e32 v124, 1.0, v124
	v_add_f32_e32 v125, 1.0, v125
	v_rcp_f32_e32 v124, v124
	v_rcp_f32_e32 v125, v125
	s_nop 1
	v_cvt_pk_bf16_f32 v124, v124, v125
	v_exp_f32_e32 v125, v126
	v_exp_f32_e32 v126, v127
	v_add_f32_e32 v120, 1.0, v120
	v_add_f32_e32 v121, 1.0, v121
	v_add_f32_e32 v125, 1.0, v125
	v_add_f32_e32 v126, 1.0, v126
	v_rcp_f32_e32 v125, v125
	v_rcp_f32_e32 v126, v126
	v_rcp_f32_e32 v120, v120
	v_rcp_f32_e32 v121, v121
	s_nop 1
	v_cvt_pk_bf16_f32 v125, v125, v126
	s_nop 1
	v_cvt_pk_bf16_f32 v126, v120, v121
	v_exp_f32_e32 v120, v122
	v_exp_f32_e32 v121, v123
	s_lshl_b32 s10, s3, 8
	v_exp_f32_e32 v116, v116
	v_add_f32_e32 v120, 1.0, v120
	v_add_f32_e32 v121, 1.0, v121
	v_rcp_f32_e32 v120, v120
	v_rcp_f32_e32 v121, v121
	v_exp_f32_e32 v117, v117
	v_lshl_add_u32 v139, s2, 8, v136
	s_ashr_i32 s11, s10, 31
	s_nop 1
	v_cvt_pk_bf16_f32 v127, v120, v121
	v_mov_b64_e32 v[120:121], s[0:1]
	v_mad_i64_i32 v[122:123], s[2:3], v139, s81, v[120:121]
	s_lshl_b64 s[10:11], s[10:11], 1
	v_lshl_add_u64 v[122:123], v[122:123], 0, s[10:11]
	v_lshl_add_u64 v[122:123], v[122:123], 0, s[90:91]
	v_add_f32_e32 v116, 1.0, v116
	v_add_f32_e32 v117, 1.0, v117
	v_lshl_add_u64 v[122:123], v[122:123], 0, v[194:195]
	v_rcp_f32_e32 v116, v116
	v_rcp_f32_e32 v117, v117
	global_store_dwordx4 v[122:123], v[124:127], off
	s_nop 1
	v_cvt_pk_bf16_f32 v116, v116, v117
	v_exp_f32_e32 v117, v118
	v_exp_f32_e32 v118, v119
	v_exp_f32_e32 v112, v112
	v_exp_f32_e32 v113, v113
	v_add_f32_e32 v117, 1.0, v117
	v_add_f32_e32 v118, 1.0, v118
	v_add_f32_e32 v112, 1.0, v112
	v_add_f32_e32 v113, 1.0, v113
	v_rcp_f32_e32 v117, v117
	v_rcp_f32_e32 v118, v118
	v_rcp_f32_e32 v112, v112
	v_rcp_f32_e32 v113, v113
	v_exp_f32_e32 v108, v108
	v_exp_f32_e32 v109, v109
	s_nop 1
	v_cvt_pk_bf16_f32 v117, v117, v118
	s_nop 1
	v_cvt_pk_bf16_f32 v118, v112, v113
	v_exp_f32_e32 v112, v114
	v_exp_f32_e32 v113, v115
	v_add_f32_e32 v108, 1.0, v108
	v_add_f32_e32 v109, 1.0, v109
	v_add_f32_e32 v112, 1.0, v112
	v_add_f32_e32 v113, 1.0, v113
	v_rcp_f32_e32 v108, v108
	v_rcp_f32_e32 v109, v109
	v_rcp_f32_e32 v112, v112
	v_rcp_f32_e32 v113, v113
	s_nop 1
	v_cvt_pk_bf16_f32 v119, v112, v113
	global_store_dwordx4 v[122:123], v[116:119], off offset:256
	s_nop 1
	v_cvt_pk_bf16_f32 v108, v108, v109
	v_exp_f32_e32 v109, v110
	v_exp_f32_e32 v110, v111
	v_exp_f32_e32 v104, v104
	v_exp_f32_e32 v105, v105
	v_add_f32_e32 v109, 1.0, v109
	v_add_f32_e32 v110, 1.0, v110
	v_add_f32_e32 v104, 1.0, v104
	v_add_f32_e32 v105, 1.0, v105
	v_rcp_f32_e32 v109, v109
	v_rcp_f32_e32 v110, v110
	v_rcp_f32_e32 v104, v104
	v_rcp_f32_e32 v105, v105
	s_nop 1
	v_cvt_pk_bf16_f32 v109, v109, v110
	s_nop 1
	v_cvt_pk_bf16_f32 v110, v104, v105
	v_exp_f32_e32 v104, v106
	v_exp_f32_e32 v105, v107
	v_exp_f32_e32 v100, v100
	v_exp_f32_e32 v101, v101
	v_add_f32_e32 v104, 1.0, v104
	v_add_f32_e32 v105, 1.0, v105
	v_or_b32_e32 v112, 16, v139
	v_rcp_f32_e32 v104, v104
	v_rcp_f32_e32 v105, v105
	s_nop 1
	v_cvt_pk_bf16_f32 v111, v104, v105
	v_mad_i64_i32 v[104:105], s[2:3], v112, s81, v[120:121]
	v_lshl_add_u64 v[104:105], v[104:105], 0, s[10:11]
	v_lshl_add_u64 v[104:105], v[104:105], 0, s[90:91]
	v_add_f32_e32 v100, 1.0, v100
	v_add_f32_e32 v101, 1.0, v101
	v_lshl_add_u64 v[104:105], v[104:105], 0, v[194:195]
	v_rcp_f32_e32 v100, v100
	v_rcp_f32_e32 v101, v101
	global_store_dwordx4 v[104:105], v[108:111], off
	s_nop 1
	v_cvt_pk_bf16_f32 v100, v100, v101
	v_exp_f32_e32 v101, v102
	v_exp_f32_e32 v102, v103
	v_exp_f32_e32 v96, v96
	v_exp_f32_e32 v97, v97
	v_add_f32_e32 v101, 1.0, v101
	v_add_f32_e32 v102, 1.0, v102
	v_add_f32_e32 v96, 1.0, v96
	v_add_f32_e32 v97, 1.0, v97
	v_rcp_f32_e32 v101, v101
	v_rcp_f32_e32 v102, v102
	v_rcp_f32_e32 v96, v96
	v_rcp_f32_e32 v97, v97
	v_exp_f32_e32 v92, v92
	v_exp_f32_e32 v93, v93
	s_nop 1
	v_cvt_pk_bf16_f32 v101, v101, v102
	s_nop 1
	v_cvt_pk_bf16_f32 v102, v96, v97
	v_exp_f32_e32 v96, v98
	v_exp_f32_e32 v97, v99
	v_add_f32_e32 v92, 1.0, v92
	v_add_f32_e32 v93, 1.0, v93
	v_add_f32_e32 v96, 1.0, v96
	v_add_f32_e32 v97, 1.0, v97
	v_rcp_f32_e32 v92, v92
	v_rcp_f32_e32 v93, v93
	v_rcp_f32_e32 v96, v96
	v_rcp_f32_e32 v97, v97
	s_nop 1
	v_cvt_pk_bf16_f32 v103, v96, v97
	global_store_dwordx4 v[104:105], v[100:103], off offset:256
	s_nop 1
	v_cvt_pk_bf16_f32 v92, v92, v93
	v_exp_f32_e32 v93, v94
	v_exp_f32_e32 v94, v95
	v_exp_f32_e32 v88, v88
	v_exp_f32_e32 v89, v89
	v_add_f32_e32 v93, 1.0, v93
	v_add_f32_e32 v94, 1.0, v94
	v_add_f32_e32 v88, 1.0, v88
	v_add_f32_e32 v89, 1.0, v89
	v_rcp_f32_e32 v93, v93
	v_rcp_f32_e32 v94, v94
	v_rcp_f32_e32 v88, v88
	v_rcp_f32_e32 v89, v89
	s_nop 1
	v_cvt_pk_bf16_f32 v93, v93, v94
	s_nop 1
	v_cvt_pk_bf16_f32 v94, v88, v89
	v_exp_f32_e32 v88, v90
	v_exp_f32_e32 v89, v91
	v_exp_f32_e32 v84, v84
	v_exp_f32_e32 v85, v85
	v_add_f32_e32 v88, 1.0, v88
	v_add_f32_e32 v89, 1.0, v89
	v_or_b32_e32 v96, 32, v139
	v_rcp_f32_e32 v88, v88
	v_rcp_f32_e32 v89, v89
	s_nop 1
	v_cvt_pk_bf16_f32 v95, v88, v89
	v_mad_i64_i32 v[88:89], s[2:3], v96, s81, v[120:121]
	v_lshl_add_u64 v[88:89], v[88:89], 0, s[10:11]
	v_lshl_add_u64 v[88:89], v[88:89], 0, s[90:91]
	v_add_f32_e32 v84, 1.0, v84
	v_add_f32_e32 v85, 1.0, v85
	v_lshl_add_u64 v[88:89], v[88:89], 0, v[194:195]
	v_rcp_f32_e32 v84, v84
	v_rcp_f32_e32 v85, v85
	global_store_dwordx4 v[88:89], v[92:95], off
	s_nop 1
	v_cvt_pk_bf16_f32 v84, v84, v85
	v_exp_f32_e32 v85, v86
	v_exp_f32_e32 v86, v87
	v_exp_f32_e32 v80, v80
	v_exp_f32_e32 v81, v81
	v_add_f32_e32 v85, 1.0, v85
	v_add_f32_e32 v86, 1.0, v86
	v_add_f32_e32 v80, 1.0, v80
	v_add_f32_e32 v81, 1.0, v81
	v_rcp_f32_e32 v85, v85
	v_rcp_f32_e32 v86, v86
	v_rcp_f32_e32 v80, v80
	v_rcp_f32_e32 v81, v81
	v_exp_f32_e32 v76, v76
	v_exp_f32_e32 v77, v77
	s_nop 1
	v_cvt_pk_bf16_f32 v85, v85, v86
	s_nop 1
	v_cvt_pk_bf16_f32 v86, v80, v81
	v_exp_f32_e32 v80, v82
	v_exp_f32_e32 v81, v83
	v_add_f32_e32 v76, 1.0, v76
	v_add_f32_e32 v77, 1.0, v77
	v_add_f32_e32 v80, 1.0, v80
	v_add_f32_e32 v81, 1.0, v81
	v_rcp_f32_e32 v76, v76
	v_rcp_f32_e32 v77, v77
	v_rcp_f32_e32 v80, v80
	v_rcp_f32_e32 v81, v81
	s_nop 1
	v_cvt_pk_bf16_f32 v87, v80, v81
	global_store_dwordx4 v[88:89], v[84:87], off offset:256
	s_nop 1
	v_cvt_pk_bf16_f32 v76, v76, v77
	v_exp_f32_e32 v77, v78
	v_exp_f32_e32 v78, v79
	v_exp_f32_e32 v72, v72
	v_exp_f32_e32 v73, v73
	v_add_f32_e32 v77, 1.0, v77
	v_add_f32_e32 v78, 1.0, v78
	v_add_f32_e32 v72, 1.0, v72
	v_add_f32_e32 v73, 1.0, v73
	v_rcp_f32_e32 v77, v77
	v_rcp_f32_e32 v78, v78
	v_rcp_f32_e32 v72, v72
	v_rcp_f32_e32 v73, v73
	s_nop 1
	v_cvt_pk_bf16_f32 v77, v77, v78
	s_nop 1
	v_cvt_pk_bf16_f32 v78, v72, v73
	v_exp_f32_e32 v72, v74
	v_exp_f32_e32 v73, v75
	v_exp_f32_e32 v68, v68
	v_exp_f32_e32 v69, v69
	v_add_f32_e32 v72, 1.0, v72
	v_add_f32_e32 v73, 1.0, v73
	v_or_b32_e32 v80, 48, v139
	v_rcp_f32_e32 v72, v72
	v_rcp_f32_e32 v73, v73
	s_nop 1
	v_cvt_pk_bf16_f32 v79, v72, v73
	v_mad_i64_i32 v[72:73], s[2:3], v80, s81, v[120:121]
	v_lshl_add_u64 v[72:73], v[72:73], 0, s[10:11]
	v_lshl_add_u64 v[72:73], v[72:73], 0, s[90:91]
	v_add_f32_e32 v68, 1.0, v68
	v_add_f32_e32 v69, 1.0, v69
	v_lshl_add_u64 v[72:73], v[72:73], 0, v[194:195]
	v_rcp_f32_e32 v68, v68
	v_rcp_f32_e32 v69, v69
	global_store_dwordx4 v[72:73], v[76:79], off
	s_nop 1
	v_cvt_pk_bf16_f32 v68, v68, v69
	v_exp_f32_e32 v69, v70
	v_exp_f32_e32 v70, v71
	v_exp_f32_e32 v64, v64
	v_exp_f32_e32 v65, v65
	v_add_f32_e32 v69, 1.0, v69
	v_add_f32_e32 v70, 1.0, v70
	v_add_f32_e32 v64, 1.0, v64
	v_add_f32_e32 v65, 1.0, v65
	v_rcp_f32_e32 v69, v69
	v_rcp_f32_e32 v70, v70
	v_rcp_f32_e32 v64, v64
	v_rcp_f32_e32 v65, v65
	v_exp_f32_e32 v60, v60
	v_exp_f32_e32 v61, v61
	s_nop 1
	v_cvt_pk_bf16_f32 v69, v69, v70
	s_nop 1
	v_cvt_pk_bf16_f32 v70, v64, v65
	v_exp_f32_e32 v64, v66
	v_exp_f32_e32 v65, v67
	v_add_f32_e32 v60, 1.0, v60
	v_add_f32_e32 v61, 1.0, v61
	v_add_f32_e32 v64, 1.0, v64
	v_add_f32_e32 v65, 1.0, v65
	v_rcp_f32_e32 v60, v60
	v_rcp_f32_e32 v61, v61
	v_rcp_f32_e32 v64, v64
	v_rcp_f32_e32 v65, v65
	s_nop 1
	v_cvt_pk_bf16_f32 v71, v64, v65
	global_store_dwordx4 v[72:73], v[68:71], off offset:256
	s_nop 1
	v_cvt_pk_bf16_f32 v60, v60, v61
	v_exp_f32_e32 v61, v62
	v_exp_f32_e32 v62, v63
	v_exp_f32_e32 v56, v56
	v_exp_f32_e32 v57, v57
	v_add_f32_e32 v61, 1.0, v61
	v_add_f32_e32 v62, 1.0, v62
	v_add_f32_e32 v56, 1.0, v56
	v_add_f32_e32 v57, 1.0, v57
	v_rcp_f32_e32 v61, v61
	v_rcp_f32_e32 v62, v62
	v_rcp_f32_e32 v56, v56
	v_rcp_f32_e32 v57, v57
	s_nop 1
	v_cvt_pk_bf16_f32 v61, v61, v62
	s_nop 1
	v_cvt_pk_bf16_f32 v62, v56, v57
	v_exp_f32_e32 v56, v58
	v_exp_f32_e32 v57, v59
	v_exp_f32_e32 v52, v52
	v_exp_f32_e32 v53, v53
	v_add_f32_e32 v56, 1.0, v56
	v_add_f32_e32 v57, 1.0, v57
	v_add_u32_e32 v64, 0x80, v139
	v_rcp_f32_e32 v56, v56
	v_rcp_f32_e32 v57, v57
	s_nop 1
	v_cvt_pk_bf16_f32 v63, v56, v57
	v_mad_i64_i32 v[56:57], s[2:3], v64, s81, v[120:121]
	v_lshl_add_u64 v[56:57], v[56:57], 0, s[10:11]
	v_lshl_add_u64 v[56:57], v[56:57], 0, s[90:91]
	v_add_f32_e32 v52, 1.0, v52
	v_add_f32_e32 v53, 1.0, v53
	v_lshl_add_u64 v[56:57], v[56:57], 0, v[194:195]
	v_rcp_f32_e32 v52, v52
	v_rcp_f32_e32 v53, v53
	global_store_dwordx4 v[56:57], v[60:63], off
	s_nop 1
	v_cvt_pk_bf16_f32 v52, v52, v53
	v_exp_f32_e32 v53, v54
	v_exp_f32_e32 v54, v55
	v_exp_f32_e32 v48, v48
	v_exp_f32_e32 v49, v49
	v_add_f32_e32 v53, 1.0, v53
	v_add_f32_e32 v54, 1.0, v54
	v_add_f32_e32 v48, 1.0, v48
	v_add_f32_e32 v49, 1.0, v49
	v_rcp_f32_e32 v53, v53
	v_rcp_f32_e32 v54, v54
	v_rcp_f32_e32 v48, v48
	v_rcp_f32_e32 v49, v49
	v_exp_f32_e32 v44, v44
	v_exp_f32_e32 v45, v45
	s_nop 1
	v_cvt_pk_bf16_f32 v53, v53, v54
	s_nop 1
	v_cvt_pk_bf16_f32 v54, v48, v49
	v_exp_f32_e32 v48, v50
	v_exp_f32_e32 v49, v51
	v_add_f32_e32 v44, 1.0, v44
	v_add_f32_e32 v45, 1.0, v45
	v_add_f32_e32 v48, 1.0, v48
	v_add_f32_e32 v49, 1.0, v49
	v_rcp_f32_e32 v44, v44
	v_rcp_f32_e32 v45, v45
	v_rcp_f32_e32 v48, v48
	v_rcp_f32_e32 v49, v49
	s_nop 1
	v_cvt_pk_bf16_f32 v55, v48, v49
	global_store_dwordx4 v[56:57], v[52:55], off offset:256
	s_nop 1
	v_cvt_pk_bf16_f32 v44, v44, v45
	v_exp_f32_e32 v45, v46
	v_exp_f32_e32 v46, v47
	v_exp_f32_e32 v40, v40
	v_exp_f32_e32 v41, v41
	v_add_f32_e32 v45, 1.0, v45
	v_add_f32_e32 v46, 1.0, v46
	v_add_f32_e32 v40, 1.0, v40
	v_add_f32_e32 v41, 1.0, v41
	v_rcp_f32_e32 v45, v45
	v_rcp_f32_e32 v46, v46
	v_rcp_f32_e32 v40, v40
	v_rcp_f32_e32 v41, v41
	s_nop 1
	v_cvt_pk_bf16_f32 v45, v45, v46
	s_nop 1
	v_cvt_pk_bf16_f32 v46, v40, v41
	v_exp_f32_e32 v40, v42
	v_exp_f32_e32 v41, v43
	v_exp_f32_e32 v36, v36
	v_exp_f32_e32 v37, v37
	v_add_f32_e32 v40, 1.0, v40
	v_add_f32_e32 v41, 1.0, v41
	v_add_u32_e32 v48, 0x90, v139
	v_rcp_f32_e32 v40, v40
	v_rcp_f32_e32 v41, v41
	s_nop 1
	v_cvt_pk_bf16_f32 v47, v40, v41
	v_mad_i64_i32 v[40:41], s[2:3], v48, s81, v[120:121]
	v_lshl_add_u64 v[40:41], v[40:41], 0, s[10:11]
	v_lshl_add_u64 v[40:41], v[40:41], 0, s[90:91]
	v_add_f32_e32 v36, 1.0, v36
	v_add_f32_e32 v37, 1.0, v37
	v_lshl_add_u64 v[40:41], v[40:41], 0, v[194:195]
	v_rcp_f32_e32 v36, v36
	v_rcp_f32_e32 v37, v37
	global_store_dwordx4 v[40:41], v[44:47], off
	s_nop 1
	v_cvt_pk_bf16_f32 v36, v36, v37
	v_exp_f32_e32 v37, v38
	v_exp_f32_e32 v38, v39
	v_exp_f32_e32 v32, v32
	v_exp_f32_e32 v33, v33
	v_add_f32_e32 v37, 1.0, v37
	v_add_f32_e32 v38, 1.0, v38
	v_add_f32_e32 v32, 1.0, v32
	v_add_f32_e32 v33, 1.0, v33
	v_rcp_f32_e32 v37, v37
	v_rcp_f32_e32 v38, v38
	v_rcp_f32_e32 v32, v32
	v_rcp_f32_e32 v33, v33
	v_exp_f32_e32 v28, v28
	v_exp_f32_e32 v29, v29
	s_nop 1
	v_cvt_pk_bf16_f32 v37, v37, v38
	s_nop 1
	v_cvt_pk_bf16_f32 v38, v32, v33
	v_exp_f32_e32 v32, v34
	v_exp_f32_e32 v33, v35
	v_add_f32_e32 v28, 1.0, v28
	v_add_f32_e32 v29, 1.0, v29
	v_add_f32_e32 v32, 1.0, v32
	v_add_f32_e32 v33, 1.0, v33
	v_rcp_f32_e32 v28, v28
	v_rcp_f32_e32 v29, v29
	v_rcp_f32_e32 v32, v32
	v_rcp_f32_e32 v33, v33
	s_nop 1
	v_cvt_pk_bf16_f32 v39, v32, v33
	global_store_dwordx4 v[40:41], v[36:39], off offset:256
	s_nop 1
	v_cvt_pk_bf16_f32 v28, v28, v29
	v_exp_f32_e32 v29, v30
	v_exp_f32_e32 v30, v31
	v_exp_f32_e32 v24, v24
	v_exp_f32_e32 v25, v25
	v_add_f32_e32 v29, 1.0, v29
	v_add_f32_e32 v30, 1.0, v30
	v_add_f32_e32 v24, 1.0, v24
	v_add_f32_e32 v25, 1.0, v25
	v_rcp_f32_e32 v29, v29
	v_rcp_f32_e32 v30, v30
	v_rcp_f32_e32 v24, v24
	v_rcp_f32_e32 v25, v25
	s_nop 1
	v_cvt_pk_bf16_f32 v29, v29, v30
	s_nop 1
	v_cvt_pk_bf16_f32 v30, v24, v25
	v_exp_f32_e32 v24, v26
	v_exp_f32_e32 v25, v27
	v_exp_f32_e32 v20, v20
	v_exp_f32_e32 v21, v21
	v_add_f32_e32 v24, 1.0, v24
	v_add_f32_e32 v25, 1.0, v25
	v_add_u32_e32 v32, 0xa0, v139
	v_rcp_f32_e32 v24, v24
	v_rcp_f32_e32 v25, v25
	s_nop 1
	v_cvt_pk_bf16_f32 v31, v24, v25
	v_mad_i64_i32 v[24:25], s[2:3], v32, s81, v[120:121]
	v_lshl_add_u64 v[24:25], v[24:25], 0, s[10:11]
	v_lshl_add_u64 v[24:25], v[24:25], 0, s[90:91]
	v_add_f32_e32 v20, 1.0, v20
	v_add_f32_e32 v21, 1.0, v21
	v_lshl_add_u64 v[24:25], v[24:25], 0, v[194:195]
	v_rcp_f32_e32 v20, v20
	v_rcp_f32_e32 v21, v21
	global_store_dwordx4 v[24:25], v[28:31], off
	s_nop 1
	v_cvt_pk_bf16_f32 v20, v20, v21
	v_exp_f32_e32 v21, v22
	v_exp_f32_e32 v22, v23
	v_exp_f32_e32 v16, v16
	v_exp_f32_e32 v17, v17
	v_add_f32_e32 v21, 1.0, v21
	v_add_f32_e32 v22, 1.0, v22
	v_add_f32_e32 v16, 1.0, v16
	v_add_f32_e32 v17, 1.0, v17
	v_rcp_f32_e32 v21, v21
	v_rcp_f32_e32 v22, v22
	v_rcp_f32_e32 v16, v16
	v_rcp_f32_e32 v17, v17
	v_exp_f32_e32 v12, v12
	v_exp_f32_e32 v13, v13
	s_nop 1
	v_cvt_pk_bf16_f32 v21, v21, v22
	s_nop 1
	v_cvt_pk_bf16_f32 v22, v16, v17
	v_exp_f32_e32 v16, v18
	v_exp_f32_e32 v17, v19
	v_add_f32_e32 v12, 1.0, v12
	v_add_f32_e32 v13, 1.0, v13
	v_add_f32_e32 v16, 1.0, v16
	v_add_f32_e32 v17, 1.0, v17
	v_rcp_f32_e32 v12, v12
	v_rcp_f32_e32 v13, v13
	v_rcp_f32_e32 v16, v16
	v_rcp_f32_e32 v17, v17
	s_nop 1
	v_cvt_pk_bf16_f32 v23, v16, v17
	global_store_dwordx4 v[24:25], v[20:23], off offset:256
	s_nop 1
	v_cvt_pk_bf16_f32 v12, v12, v13
	v_exp_f32_e32 v13, v14
	v_exp_f32_e32 v14, v15
	v_exp_f32_e32 v8, v8
	v_exp_f32_e32 v9, v9
	v_add_f32_e32 v13, 1.0, v13
	v_add_f32_e32 v14, 1.0, v14
	v_add_f32_e32 v8, 1.0, v8
	v_add_f32_e32 v9, 1.0, v9
	v_rcp_f32_e32 v13, v13
	v_rcp_f32_e32 v14, v14
	v_rcp_f32_e32 v8, v8
	v_rcp_f32_e32 v9, v9
	s_nop 1
	v_cvt_pk_bf16_f32 v13, v13, v14
	s_nop 1
	v_cvt_pk_bf16_f32 v14, v8, v9
	v_exp_f32_e32 v8, v10
	v_exp_f32_e32 v9, v11
	v_exp_f32_e32 v4, v4
	v_exp_f32_e32 v5, v5
	v_add_f32_e32 v8, 1.0, v8
	v_add_f32_e32 v9, 1.0, v9
	v_add_u32_e32 v16, 0xb0, v139
	v_rcp_f32_e32 v8, v8
	v_rcp_f32_e32 v9, v9
	s_nop 1
	v_cvt_pk_bf16_f32 v15, v8, v9
	v_mad_i64_i32 v[8:9], s[2:3], v16, s81, v[120:121]
	v_lshl_add_u64 v[8:9], v[8:9], 0, s[10:11]
	v_lshl_add_u64 v[8:9], v[8:9], 0, s[90:91]
	v_add_f32_e32 v4, 1.0, v4
	v_add_f32_e32 v5, 1.0, v5
	v_lshl_add_u64 v[8:9], v[8:9], 0, v[194:195]
	v_rcp_f32_e32 v4, v4
	v_rcp_f32_e32 v5, v5
	global_store_dwordx4 v[8:9], v[12:15], off
	s_nop 1
	v_cvt_pk_bf16_f32 v4, v4, v5
	v_exp_f32_e32 v5, v6
	v_exp_f32_e32 v6, v7
	v_exp_f32_e32 v0, v0
	v_exp_f32_e32 v1, v1
	v_add_f32_e32 v5, 1.0, v5
	v_add_f32_e32 v6, 1.0, v6
	v_add_f32_e32 v0, 1.0, v0
	v_add_f32_e32 v1, 1.0, v1
	v_rcp_f32_e32 v5, v5
	v_rcp_f32_e32 v6, v6
	v_rcp_f32_e32 v0, v0
	v_rcp_f32_e32 v1, v1
	s_nop 1
	v_cvt_pk_bf16_f32 v5, v5, v6
	s_nop 1
	v_cvt_pk_bf16_f32 v6, v0, v1
	v_exp_f32_e32 v0, v2
	v_exp_f32_e32 v1, v3
	s_and_b64 vcc, exec, s[4:5]
	s_mov_b32 s2, s30
	v_add_f32_e32 v0, 1.0, v0
	v_add_f32_e32 v1, 1.0, v1
	s_mov_b32 s3, s29
	s_mov_b64 s[12:13], s[8:9]
	s_mov_b64 s[10:11], s[6:7]
	v_rcp_f32_e32 v0, v0
	v_rcp_f32_e32 v1, v1
	s_nop 1
	v_cvt_pk_bf16_f32 v7, v0, v1
	global_store_dwordx4 v[8:9], v[4:7], off offset:256
	s_cbranch_vccz .LBB0_601
	s_waitcnt vmcnt(0)
	s_cmpk_gt_u32 s16, 0xff
	s_cbranch_scc1 .LBB0_608
	s_barrier

.LBB0_670:
	s_add_i32 s44, s14, 2
	s_add_u32 s15, s8, 0xfffc0080
	s_addc_u32 s16, s9, -1
	s_add_i32 s45, 0, 0x10000
	v_add_u32_e32 v140, s45, v237
	ds_read_b128 v[128:131], v140
	ds_read_b128 v[132:135], v140 offset:1024
	ds_read_b128 v[136:139], v140 offset:2048
	ds_read_b128 v[140:143], v140 offset:3072
	s_cmp_eq_u32 s41, s14
	s_cselect_b32 s14, s12, s42
	s_cselect_b32 s17, s11, s16
	s_cselect_b32 s16, s10, s15
	s_cselect_b32 s15, s13, s43
	v_lshl_add_u64 v[176:177], s[8:9], 0, v[206:207]
	s_add_i32 m0, s24, 0xc000
	ds_read_b128 v[144:147], v242
	ds_read_b128 v[148:151], v242 offset:1024
	ds_read_b128 v[152:155], v242 offset:2048
	ds_read_b128 v[156:159], v242 offset:3072
	ds_read_b128 v[160:163], v242 offset:4096
	ds_read_b128 v[164:167], v242 offset:5120
	ds_read_b128 v[168:171], v242 offset:6144
	ds_read_b128 v[172:175], v242 offset:7168
	global_load_lds_dwordx4 v[176:177], off
	v_lshl_add_u64 v[176:177], s[8:9], 0, v[208:209]
	s_add_i32 m0, s24, 0xe000
	s_nop 0
	global_load_lds_dwordx4 v[176:177], off
	s_waitcnt lgkmcnt(8)
	s_barrier
	s_waitcnt lgkmcnt(0)
	s_setprio 1
	s_waitcnt lgkmcnt(0)
	v_mfma_f32_16x16x32_bf16 v[124:127], v[128:131], v[144:147], v[124:127]
	v_mfma_f32_16x16x32_bf16 v[120:123], v[136:139], v[144:147], v[120:123]
	v_mfma_f32_16x16x32_bf16 v[112:115], v[128:131], v[152:155], v[112:115]
	v_mfma_f32_16x16x32_bf16 v[104:107], v[136:139], v[152:155], v[104:107]
	v_mfma_f32_16x16x32_bf16 v[96:99], v[128:131], v[160:163], v[96:99]
	v_mfma_f32_16x16x32_bf16 v[88:91], v[136:139], v[160:163], v[88:91]
	v_mfma_f32_16x16x32_bf16 v[80:83], v[128:131], v[168:171], v[80:83]
	v_mfma_f32_16x16x32_bf16 v[72:75], v[136:139], v[168:171], v[72:75]
	v_mfma_f32_16x16x32_bf16 v[124:127], v[132:135], v[148:151], v[124:127]
	v_mfma_f32_16x16x32_bf16 v[120:123], v[140:143], v[148:151], v[120:123]
	v_mfma_f32_16x16x32_bf16 v[112:115], v[132:135], v[156:159], v[112:115]
	v_mfma_f32_16x16x32_bf16 v[104:107], v[140:143], v[156:159], v[104:107]
	v_mfma_f32_16x16x32_bf16 v[96:99], v[132:135], v[164:167], v[96:99]
	v_mfma_f32_16x16x32_bf16 v[88:91], v[140:143], v[164:167], v[88:91]
	v_mfma_f32_16x16x32_bf16 v[80:83], v[132:135], v[172:175], v[80:83]
	v_mfma_f32_16x16x32_bf16 v[72:75], v[140:143], v[172:175], v[72:75]
	s_setprio 0
	s_barrier
	s_add_i32 s48, 0, 0x14000
	s_add_i32 s45, s45, s23
	v_add_u32_e32 v188, s48, v237
	v_lshl_add_u64 v[192:193], s[14:15], 0, v[194:195]
	s_mov_b32 m0, s45
	ds_read_b128 v[176:179], v188
	ds_read_b128 v[180:183], v188 offset:1024
	ds_read_b128 v[184:187], v188 offset:2048
	ds_read_b128 v[188:191], v188 offset:3072
	global_load_lds_dwordx4 v[192:193], off
	v_lshl_add_u64 v[210:211], s[14:15], 0, v[204:205]
	s_add_i32 m0, s45, 0x2000
	s_nop 0
	global_load_lds_dwordx4 v[210:211], off
	s_barrier
	s_waitcnt lgkmcnt(0)
	s_setprio 1
	s_waitcnt lgkmcnt(0)
	v_mfma_f32_16x16x32_bf16 v[116:119], v[176:179], v[144:147], v[116:119]
	v_mfma_f32_16x16x32_bf16 v[108:111], v[184:187], v[144:147], v[108:111]
	v_mfma_f32_16x16x32_bf16 v[100:103], v[176:179], v[152:155], v[100:103]
	v_mfma_f32_16x16x32_bf16 v[92:95], v[184:187], v[152:155], v[92:95]
	v_mfma_f32_16x16x32_bf16 v[84:87], v[176:179], v[160:163], v[84:87]
	v_mfma_f32_16x16x32_bf16 v[76:79], v[184:187], v[160:163], v[76:79]
	v_mfma_f32_16x16x32_bf16 v[68:71], v[176:179], v[168:171], v[68:71]
	v_mfma_f32_16x16x32_bf16 v[64:67], v[184:187], v[168:171], v[64:67]
	v_mfma_f32_16x16x32_bf16 v[116:119], v[180:183], v[148:151], v[116:119]
	v_mfma_f32_16x16x32_bf16 v[108:111], v[188:191], v[148:151], v[108:111]
	v_mfma_f32_16x16x32_bf16 v[100:103], v[180:183], v[156:159], v[100:103]
	v_mfma_f32_16x16x32_bf16 v[92:95], v[188:191], v[156:159], v[92:95]
	v_mfma_f32_16x16x32_bf16 v[84:87], v[180:183], v[164:167], v[84:87]
	v_mfma_f32_16x16x32_bf16 v[76:79], v[188:191], v[164:167], v[76:79]
	v_mfma_f32_16x16x32_bf16 v[68:71], v[180:183], v[172:175], v[68:71]
	v_mfma_f32_16x16x32_bf16 v[64:67], v[188:191], v[172:175], v[64:67]
	s_setprio 0
	s_mov_b32 m0, s24
	v_lshl_add_u64 v[212:213], s[16:17], 0, v[194:195]
	s_barrier
	ds_read_b128 v[144:147], v242 offset:16384
	ds_read_b128 v[148:151], v242 offset:17408
	ds_read_b128 v[152:155], v242 offset:18432
	ds_read_b128 v[156:159], v242 offset:19456
	ds_read_b128 v[160:163], v242 offset:20480
	ds_read_b128 v[164:167], v242 offset:21504
	ds_read_b128 v[168:171], v242 offset:22528
	ds_read_b128 v[172:175], v242 offset:23552
	global_load_lds_dwordx4 v[212:213], off
	v_lshl_add_u64 v[214:215], s[16:17], 0, v[204:205]
	s_mov_b32 m0, s25
	s_nop 0
	global_load_lds_dwordx4 v[214:215], off
	s_barrier
	s_waitcnt lgkmcnt(0)
	s_setprio 1
	s_waitcnt lgkmcnt(0)
	v_mfma_f32_16x16x32_bf16 v[60:63], v[128:131], v[144:147], v[60:63]
	v_mfma_f32_16x16x32_bf16 v[56:59], v[136:139], v[144:147], v[56:59]
	v_mfma_f32_16x16x32_bf16 v[48:51], v[128:131], v[152:155], v[48:51]
	v_mfma_f32_16x16x32_bf16 v[40:43], v[136:139], v[152:155], v[40:43]
	v_mfma_f32_16x16x32_bf16 v[32:35], v[128:131], v[160:163], v[32:35]
	v_mfma_f32_16x16x32_bf16 v[24:27], v[136:139], v[160:163], v[24:27]
	v_mfma_f32_16x16x32_bf16 v[16:19], v[128:131], v[168:171], v[16:19]
	v_mfma_f32_16x16x32_bf16 v[8:11], v[136:139], v[168:171], v[8:11]
	v_mfma_f32_16x16x32_bf16 v[60:63], v[132:135], v[148:151], v[60:63]
	v_mfma_f32_16x16x32_bf16 v[56:59], v[140:143], v[148:151], v[56:59]
	v_mfma_f32_16x16x32_bf16 v[48:51], v[132:135], v[156:159], v[48:51]
	v_mfma_f32_16x16x32_bf16 v[40:43], v[140:143], v[156:159], v[40:43]
	v_mfma_f32_16x16x32_bf16 v[32:35], v[132:135], v[164:167], v[32:35]
	v_mfma_f32_16x16x32_bf16 v[24:27], v[140:143], v[164:167], v[24:27]
	v_mfma_f32_16x16x32_bf16 v[16:19], v[132:135], v[172:175], v[16:19]
	v_mfma_f32_16x16x32_bf16 v[8:11], v[140:143], v[172:175], v[8:11]
	s_setprio 0
	s_barrier
	s_add_u32 s46, s14, 0x40000
	s_addc_u32 s47, s15, 0
	s_add_i32 s45, s48, s23
	v_lshl_add_u64 v[128:129], s[46:47], 0, v[194:195]
	s_mov_b32 m0, s45
	s_nop 0
	global_load_lds_dwordx4 v[128:129], off
	v_lshl_add_u64 v[128:129], s[46:47], 0, v[204:205]
	s_add_i32 m0, s45, 0x2000
	s_nop 0
	global_load_lds_dwordx4 v[128:129], off
	s_add_i32 s45, 0, 0x18000
	v_add_u32_e32 v140, s45, v237
	ds_read_b128 v[128:131], v140
	ds_read_b128 v[132:135], v140 offset:1024
	ds_read_b128 v[136:139], v140 offset:2048
	ds_read_b128 v[140:143], v140 offset:3072
	s_waitcnt vmcnt(6)
	s_barrier
	s_setprio 1
	v_mfma_f32_16x16x32_bf16 v[52:55], v[176:179], v[144:147], v[52:55]
	v_mfma_f32_16x16x32_bf16 v[44:47], v[184:187], v[144:147], v[44:47]
	v_mfma_f32_16x16x32_bf16 v[36:39], v[176:179], v[152:155], v[36:39]
	v_mfma_f32_16x16x32_bf16 v[28:31], v[184:187], v[152:155], v[28:31]
	v_mfma_f32_16x16x32_bf16 v[20:23], v[176:179], v[160:163], v[20:23]
	v_mfma_f32_16x16x32_bf16 v[12:15], v[184:187], v[160:163], v[12:15]
	v_mfma_f32_16x16x32_bf16 v[4:7], v[176:179], v[168:171], v[4:7]
	v_mfma_f32_16x16x32_bf16 v[0:3], v[184:187], v[168:171], v[0:3]
	v_mfma_f32_16x16x32_bf16 v[52:55], v[180:183], v[148:151], v[52:55]
	v_mfma_f32_16x16x32_bf16 v[44:47], v[188:191], v[148:151], v[44:47]
	v_mfma_f32_16x16x32_bf16 v[36:39], v[180:183], v[156:159], v[36:39]
	v_mfma_f32_16x16x32_bf16 v[28:31], v[188:191], v[156:159], v[28:31]
	v_mfma_f32_16x16x32_bf16 v[20:23], v[180:183], v[164:167], v[20:23]
	v_mfma_f32_16x16x32_bf16 v[12:15], v[188:191], v[164:167], v[12:15]
	v_mfma_f32_16x16x32_bf16 v[4:7], v[180:183], v[172:175], v[4:7]
	v_mfma_f32_16x16x32_bf16 v[0:3], v[188:191], v[172:175], v[0:3]
	s_setprio 0
	s_barrier
	s_add_u32 s16, s16, 0x40000
	s_addc_u32 s17, s17, 0
	s_mov_b32 m0, s26
	v_lshl_add_u64 v[176:177], s[16:17], 0, v[194:195]
	ds_read_b128 v[144:147], v242 offset:32768
	ds_read_b128 v[148:151], v242 offset:33792
	ds_read_b128 v[152:155], v242 offset:34816
	ds_read_b128 v[156:159], v242 offset:35840
	ds_read_b128 v[160:163], v242 offset:36864
	ds_read_b128 v[164:167], v242 offset:37888
	ds_read_b128 v[168:171], v242 offset:38912
	ds_read_b128 v[172:175], v242 offset:39936
	global_load_lds_dwordx4 v[176:177], off
	v_lshl_add_u64 v[176:177], s[16:17], 0, v[204:205]
	s_mov_b32 m0, s27
	s_nop 0
	global_load_lds_dwordx4 v[176:177], off
	s_waitcnt lgkmcnt(8)
	s_barrier
	s_waitcnt lgkmcnt(0)
	s_setprio 1
	s_waitcnt lgkmcnt(0)
	v_mfma_f32_16x16x32_bf16 v[124:127], v[128:131], v[144:147], v[124:127]
	v_mfma_f32_16x16x32_bf16 v[120:123], v[136:139], v[144:147], v[120:123]
	v_mfma_f32_16x16x32_bf16 v[112:115], v[128:131], v[152:155], v[112:115]
	v_mfma_f32_16x16x32_bf16 v[104:107], v[136:139], v[152:155], v[104:107]
	v_mfma_f32_16x16x32_bf16 v[96:99], v[128:131], v[160:163], v[96:99]
	v_mfma_f32_16x16x32_bf16 v[88:91], v[136:139], v[160:163], v[88:91]
	v_mfma_f32_16x16x32_bf16 v[80:83], v[128:131], v[168:171], v[80:83]
	v_mfma_f32_16x16x32_bf16 v[72:75], v[136:139], v[168:171], v[72:75]
	v_mfma_f32_16x16x32_bf16 v[124:127], v[132:135], v[148:151], v[124:127]
	v_mfma_f32_16x16x32_bf16 v[120:123], v[140:143], v[148:151], v[120:123]
	v_mfma_f32_16x16x32_bf16 v[112:115], v[132:135], v[156:159], v[112:115]
	v_mfma_f32_16x16x32_bf16 v[104:107], v[140:143], v[156:159], v[104:107]
	v_mfma_f32_16x16x32_bf16 v[96:99], v[132:135], v[164:167], v[96:99]
	v_mfma_f32_16x16x32_bf16 v[88:91], v[140:143], v[164:167], v[88:91]
	v_mfma_f32_16x16x32_bf16 v[80:83], v[132:135], v[172:175], v[80:83]
	v_mfma_f32_16x16x32_bf16 v[72:75], v[140:143], v[172:175], v[72:75]
	s_setprio 0
	s_barrier
	s_add_i32 s16, 0, 0x1c000
	s_add_i32 s17, s45, s23
	v_add_u32_e32 v188, s16, v237
	v_lshl_add_u64 v[192:193], v[192:193], 0, s[82:83]
	s_mov_b32 m0, s17
	ds_read_b128 v[176:179], v188
	ds_read_b128 v[180:183], v188 offset:1024
	ds_read_b128 v[184:187], v188 offset:2048
	ds_read_b128 v[188:191], v188 offset:3072
	global_load_lds_dwordx4 v[192:193], off
	v_lshl_add_u64 v[192:193], v[210:211], 0, s[82:83]
	s_add_i32 m0, s17, 0x2000
	s_nop 0
	global_load_lds_dwordx4 v[192:193], off
	s_barrier
	s_waitcnt lgkmcnt(0)
	s_setprio 1
	s_waitcnt lgkmcnt(0)
	v_mfma_f32_16x16x32_bf16 v[116:119], v[176:179], v[144:147], v[116:119]
	v_mfma_f32_16x16x32_bf16 v[108:111], v[184:187], v[144:147], v[108:111]
	v_mfma_f32_16x16x32_bf16 v[100:103], v[176:179], v[152:155], v[100:103]
	v_mfma_f32_16x16x32_bf16 v[92:95], v[184:187], v[152:155], v[92:95]
	v_mfma_f32_16x16x32_bf16 v[84:87], v[176:179], v[160:163], v[84:87]
	v_mfma_f32_16x16x32_bf16 v[76:79], v[184:187], v[160:163], v[76:79]
	v_mfma_f32_16x16x32_bf16 v[68:71], v[176:179], v[168:171], v[68:71]
	v_mfma_f32_16x16x32_bf16 v[64:67], v[184:187], v[168:171], v[64:67]
	v_mfma_f32_16x16x32_bf16 v[116:119], v[180:183], v[148:151], v[116:119]
	v_mfma_f32_16x16x32_bf16 v[108:111], v[188:191], v[148:151], v[108:111]
	v_mfma_f32_16x16x32_bf16 v[100:103], v[180:183], v[156:159], v[100:103]
	v_mfma_f32_16x16x32_bf16 v[92:95], v[188:191], v[156:159], v[92:95]
	v_mfma_f32_16x16x32_bf16 v[84:87], v[180:183], v[164:167], v[84:87]
	v_mfma_f32_16x16x32_bf16 v[76:79], v[188:191], v[164:167], v[76:79]
	v_mfma_f32_16x16x32_bf16 v[68:71], v[180:183], v[172:175], v[68:71]
	v_mfma_f32_16x16x32_bf16 v[64:67], v[188:191], v[172:175], v[64:67]
	s_setprio 0
	s_mov_b32 m0, s28
	v_lshl_add_u64 v[192:193], v[212:213], 0, s[82:83]
	s_barrier
	ds_read_b128 v[144:147], v242 offset:49152
	ds_read_b128 v[148:151], v242 offset:50176
	ds_read_b128 v[152:155], v242 offset:51200
	ds_read_b128 v[156:159], v242 offset:52224
	ds_read_b128 v[160:163], v242 offset:53248
	ds_read_b128 v[164:167], v242 offset:54272
	ds_read_b128 v[168:171], v242 offset:55296
	ds_read_b128 v[172:175], v242 offset:56320
	global_load_lds_dwordx4 v[192:193], off
	v_lshl_add_u64 v[192:193], v[214:215], 0, s[82:83]
	s_mov_b32 m0, s29
	s_nop 0
	global_load_lds_dwordx4 v[192:193], off
	s_barrier
	s_waitcnt lgkmcnt(0)
	s_setprio 1
	s_waitcnt lgkmcnt(0)
	v_mfma_f32_16x16x32_bf16 v[60:63], v[128:131], v[144:147], v[60:63]
	v_mfma_f32_16x16x32_bf16 v[56:59], v[136:139], v[144:147], v[56:59]
	v_mfma_f32_16x16x32_bf16 v[48:51], v[128:131], v[152:155], v[48:51]
	v_mfma_f32_16x16x32_bf16 v[40:43], v[136:139], v[152:155], v[40:43]
	v_mfma_f32_16x16x32_bf16 v[32:35], v[128:131], v[160:163], v[32:35]
	v_mfma_f32_16x16x32_bf16 v[24:27], v[136:139], v[160:163], v[24:27]
	v_mfma_f32_16x16x32_bf16 v[16:19], v[128:131], v[168:171], v[16:19]
	v_mfma_f32_16x16x32_bf16 v[8:11], v[136:139], v[168:171], v[8:11]
	v_mfma_f32_16x16x32_bf16 v[60:63], v[132:135], v[148:151], v[60:63]
	v_mfma_f32_16x16x32_bf16 v[56:59], v[140:143], v[148:151], v[56:59]
	v_mfma_f32_16x16x32_bf16 v[48:51], v[132:135], v[156:159], v[48:51]
	v_mfma_f32_16x16x32_bf16 v[40:43], v[140:143], v[156:159], v[40:43]
	v_mfma_f32_16x16x32_bf16 v[32:35], v[132:135], v[164:167], v[32:35]
	v_mfma_f32_16x16x32_bf16 v[24:27], v[140:143], v[164:167], v[24:27]
	v_mfma_f32_16x16x32_bf16 v[16:19], v[132:135], v[172:175], v[16:19]
	v_mfma_f32_16x16x32_bf16 v[8:11], v[140:143], v[172:175], v[8:11]
	s_setprio 0
	s_barrier
	s_add_u32 s14, s14, 0x40080
	s_addc_u32 s15, s15, 0
	s_add_i32 s16, s16, s23
	v_lshl_add_u64 v[128:129], s[14:15], 0, v[194:195]
	s_mov_b32 m0, s16
	s_nop 0
	global_load_lds_dwordx4 v[128:129], off
	v_lshl_add_u64 v[128:129], s[14:15], 0, v[204:205]
	s_add_i32 m0, s16, 0x2000
	s_nop 0
	global_load_lds_dwordx4 v[128:129], off
	s_waitcnt vmcnt(6)
	s_barrier
	s_setprio 1
	v_mfma_f32_16x16x32_bf16 v[52:55], v[176:179], v[144:147], v[52:55]
	v_mfma_f32_16x16x32_bf16 v[44:47], v[184:187], v[144:147], v[44:47]
	v_mfma_f32_16x16x32_bf16 v[36:39], v[176:179], v[152:155], v[36:39]
	v_mfma_f32_16x16x32_bf16 v[28:31], v[184:187], v[152:155], v[28:31]
	v_mfma_f32_16x16x32_bf16 v[20:23], v[176:179], v[160:163], v[20:23]
	v_mfma_f32_16x16x32_bf16 v[12:15], v[184:187], v[160:163], v[12:15]
	v_mfma_f32_16x16x32_bf16 v[4:7], v[176:179], v[168:171], v[4:7]
	v_mfma_f32_16x16x32_bf16 v[0:3], v[184:187], v[168:171], v[0:3]
	v_mfma_f32_16x16x32_bf16 v[52:55], v[180:183], v[148:151], v[52:55]
	v_mfma_f32_16x16x32_bf16 v[44:47], v[188:191], v[148:151], v[44:47]
	v_mfma_f32_16x16x32_bf16 v[36:39], v[180:183], v[156:159], v[36:39]
	v_mfma_f32_16x16x32_bf16 v[28:31], v[188:191], v[156:159], v[28:31]
	v_mfma_f32_16x16x32_bf16 v[20:23], v[180:183], v[164:167], v[20:23]
	v_mfma_f32_16x16x32_bf16 v[12:15], v[188:191], v[164:167], v[12:15]
	v_mfma_f32_16x16x32_bf16 v[4:7], v[180:183], v[172:175], v[4:7]
	v_mfma_f32_16x16x32_bf16 v[0:3], v[188:191], v[172:175], v[0:3]
	s_setprio 0
	s_add_u32 s8, s8, 0x100
	s_addc_u32 s9, s9, 0
	s_add_u32 s42, s42, 0x100
	s_addc_u32 s43, s43, 0
	s_cmp_ge_i32 s44, s40
	s_mov_b32 s14, s44
	s_barrier
	s_cbranch_scc0 .LBB0_670
	s_lshl_b32 s8, s37, 10
	s_ashr_i32 s9, s8, 31
	s_cmp_gt_i32 s37, 0
	s_cselect_b64 s[16:17], -1, 0
	s_lshl_b32 s39, s39, 8
	s_lshl_b64 s[8:9], s[8:9], 1
	s_add_u32 s14, s3, s8
	s_addc_u32 s15, s18, s9
	v_add_u32_e32 v210, s39, v236
	v_lshl_or_b32 v212, s38, 8, v241
	v_mov_b64_e32 v[128:129], s[14:15]
	v_mad_i64_i32 v[128:129], s[8:9], v210, s81, v[128:129]
	v_ashrrev_i32_e32 v213, 31, v212
	v_lshl_add_u64 v[130:131], v[212:213], 1, v[128:129]
	global_load_dwordx4 v[186:189], v[130:131], off
	v_ashrrev_i32_e32 v211, 31, v210
	v_lshlrev_b64 v[128:129], 11, v[210:211]
	v_lshl_add_u64 v[214:215], s[0:1], 0, v[128:129]
	s_cmp_lt_i32 s37, 1
	v_lshl_add_u64 v[128:129], v[212:213], 1, v[214:215]
	s_cbranch_scc1 .LBB0_673
	global_load_dwordx4 v[190:193], v[128:129], off
	s_branch .LBB0_674

.LBB0_766:
	s_add_u32 s10, s8, 0xfffc0080
	s_addc_u32 s11, s9, -1
	s_add_i32 s38, 0, 0x10000
	v_add_u32_e32 v146, s38, v151
	ds_read_b128 v[120:123], v146
	ds_read_b128 v[124:127], v146 offset:1024
	ds_read_b128 v[142:145], v146 offset:2048
	ds_read_b128 v[146:149], v146 offset:3072
	s_cmp_eq_u32 s37, 12
	s_cselect_b32 s13, s1, s11
	s_cselect_b32 s12, s0, s10
	s_cselect_b32 s11, s7, s36
	s_cselect_b32 s10, s6, s35
	v_lshl_add_u64 v[186:187], s[8:9], 0, v[138:139]
	s_add_i32 m0, s20, 0xc000
	ds_read_b128 v[154:157], v153
	ds_read_b128 v[158:161], v153 offset:1024
	ds_read_b128 v[162:165], v153 offset:2048
	ds_read_b128 v[166:169], v153 offset:3072
	ds_read_b128 v[170:173], v153 offset:4096
	ds_read_b128 v[174:177], v153 offset:5120
	ds_read_b128 v[178:181], v153 offset:6144
	ds_read_b128 v[182:185], v153 offset:7168
	global_load_lds_dwordx4 v[186:187], off
	v_lshl_add_u64 v[186:187], s[8:9], 0, v[140:141]
	s_add_i32 m0, s20, 0xe000
	s_nop 0
	global_load_lds_dwordx4 v[186:187], off
	s_waitcnt lgkmcnt(8)
	s_barrier
	s_waitcnt lgkmcnt(0)
	s_setprio 1
	s_waitcnt lgkmcnt(0)
	v_mfma_f32_16x16x32_bf16 v[132:135], v[120:123], v[154:157], v[132:135]
	v_mfma_f32_16x16x32_bf16 v[128:131], v[142:145], v[154:157], v[128:131]
	v_mfma_f32_16x16x32_bf16 v[116:119], v[120:123], v[162:165], v[116:119]
	v_mfma_f32_16x16x32_bf16 v[112:115], v[142:145], v[162:165], v[112:115]
	v_mfma_f32_16x16x32_bf16 v[108:111], v[120:123], v[170:173], v[108:111]
	v_mfma_f32_16x16x32_bf16 v[104:107], v[142:145], v[170:173], v[104:107]
	v_mfma_f32_16x16x32_bf16 v[100:103], v[120:123], v[178:181], v[100:103]
	v_mfma_f32_16x16x32_bf16 v[96:99], v[142:145], v[178:181], v[96:99]
	v_mfma_f32_16x16x32_bf16 v[132:135], v[124:127], v[158:161], v[132:135]
	v_mfma_f32_16x16x32_bf16 v[128:131], v[146:149], v[158:161], v[128:131]
	v_mfma_f32_16x16x32_bf16 v[116:119], v[124:127], v[166:169], v[116:119]
	v_mfma_f32_16x16x32_bf16 v[112:115], v[146:149], v[166:169], v[112:115]
	v_mfma_f32_16x16x32_bf16 v[108:111], v[124:127], v[174:177], v[108:111]
	v_mfma_f32_16x16x32_bf16 v[104:107], v[146:149], v[174:177], v[104:107]
	v_mfma_f32_16x16x32_bf16 v[100:103], v[124:127], v[182:185], v[100:103]
	v_mfma_f32_16x16x32_bf16 v[96:99], v[146:149], v[182:185], v[96:99]
	s_setprio 0
	s_barrier
	s_add_i32 s40, 0, 0x14000
	s_add_i32 s38, s38, s19
	v_add_u32_e32 v208, s40, v151
	v_lshl_add_u64 v[212:213], s[10:11], 0, v[194:195]
	s_mov_b32 m0, s38
	ds_read_b128 v[186:189], v208
	ds_read_b128 v[190:193], v208 offset:1024
	ds_read_b128 v[204:207], v208 offset:2048
	ds_read_b128 v[208:211], v208 offset:3072
	global_load_lds_dwordx4 v[212:213], off
	v_lshl_add_u64 v[214:215], s[10:11], 0, v[136:137]
	s_add_i32 m0, s38, 0x2000
	s_nop 0
	global_load_lds_dwordx4 v[214:215], off
	s_barrier
	s_waitcnt lgkmcnt(0)
	s_setprio 1
	s_waitcnt lgkmcnt(0)
	v_mfma_f32_16x16x32_bf16 v[64:67], v[186:189], v[154:157], v[64:67]
	v_mfma_f32_16x16x32_bf16 v[56:59], v[204:207], v[154:157], v[56:59]
	v_mfma_f32_16x16x32_bf16 v[52:55], v[186:189], v[162:165], v[52:55]
	v_mfma_f32_16x16x32_bf16 v[48:51], v[204:207], v[162:165], v[48:51]
	v_mfma_f32_16x16x32_bf16 v[44:47], v[186:189], v[170:173], v[44:47]
	v_mfma_f32_16x16x32_bf16 v[40:43], v[204:207], v[170:173], v[40:43]
	v_mfma_f32_16x16x32_bf16 v[36:39], v[186:189], v[178:181], v[36:39]
	v_mfma_f32_16x16x32_bf16 v[32:35], v[204:207], v[178:181], v[32:35]
	v_mfma_f32_16x16x32_bf16 v[64:67], v[190:193], v[158:161], v[64:67]
	v_mfma_f32_16x16x32_bf16 v[56:59], v[208:211], v[158:161], v[56:59]
	v_mfma_f32_16x16x32_bf16 v[52:55], v[190:193], v[166:169], v[52:55]
	v_mfma_f32_16x16x32_bf16 v[48:51], v[208:211], v[166:169], v[48:51]
	v_mfma_f32_16x16x32_bf16 v[44:47], v[190:193], v[174:177], v[44:47]
	v_mfma_f32_16x16x32_bf16 v[40:43], v[208:211], v[174:177], v[40:43]
	v_mfma_f32_16x16x32_bf16 v[36:39], v[190:193], v[182:185], v[36:39]
	v_mfma_f32_16x16x32_bf16 v[32:35], v[208:211], v[182:185], v[32:35]
	s_setprio 0
	s_mov_b32 m0, s20
	v_lshl_add_u64 v[216:217], s[12:13], 0, v[194:195]
	s_barrier
	ds_read_b128 v[154:157], v153 offset:16384
	ds_read_b128 v[158:161], v153 offset:17408
	ds_read_b128 v[162:165], v153 offset:18432
	ds_read_b128 v[166:169], v153 offset:19456
	ds_read_b128 v[170:173], v153 offset:20480
	ds_read_b128 v[174:177], v153 offset:21504
	ds_read_b128 v[178:181], v153 offset:22528
	ds_read_b128 v[182:185], v153 offset:23552
	global_load_lds_dwordx4 v[216:217], off
	v_lshl_add_u64 v[236:237], s[12:13], 0, v[136:137]
	s_mov_b32 m0, s21
	s_nop 0
	global_load_lds_dwordx4 v[236:237], off
	s_barrier
	s_waitcnt lgkmcnt(0)
	s_setprio 1
	s_waitcnt lgkmcnt(0)
	v_mfma_f32_16x16x32_bf16 v[92:95], v[120:123], v[154:157], v[92:95]
	v_mfma_f32_16x16x32_bf16 v[88:91], v[142:145], v[154:157], v[88:91]
	v_mfma_f32_16x16x32_bf16 v[84:87], v[120:123], v[162:165], v[84:87]
	v_mfma_f32_16x16x32_bf16 v[80:83], v[142:145], v[162:165], v[80:83]
	v_mfma_f32_16x16x32_bf16 v[76:79], v[120:123], v[170:173], v[76:79]
	v_mfma_f32_16x16x32_bf16 v[72:75], v[142:145], v[170:173], v[72:75]
	v_mfma_f32_16x16x32_bf16 v[68:71], v[120:123], v[178:181], v[68:71]
	v_mfma_f32_16x16x32_bf16 v[60:63], v[142:145], v[178:181], v[60:63]
	v_mfma_f32_16x16x32_bf16 v[92:95], v[124:127], v[158:161], v[92:95]
	v_mfma_f32_16x16x32_bf16 v[88:91], v[146:149], v[158:161], v[88:91]
	v_mfma_f32_16x16x32_bf16 v[84:87], v[124:127], v[166:169], v[84:87]
	v_mfma_f32_16x16x32_bf16 v[80:83], v[146:149], v[166:169], v[80:83]
	v_mfma_f32_16x16x32_bf16 v[76:79], v[124:127], v[174:177], v[76:79]
	v_mfma_f32_16x16x32_bf16 v[72:75], v[146:149], v[174:177], v[72:75]
	v_mfma_f32_16x16x32_bf16 v[68:71], v[124:127], v[182:185], v[68:71]
	v_mfma_f32_16x16x32_bf16 v[60:63], v[146:149], v[182:185], v[60:63]
	s_setprio 0
	s_barrier
	s_add_u32 s38, s10, 0x40000
	s_addc_u32 s39, s11, 0
	s_add_i32 s40, s40, s19
	v_lshl_add_u64 v[120:121], s[38:39], 0, v[194:195]
	s_mov_b32 m0, s40
	s_nop 0
	global_load_lds_dwordx4 v[120:121], off
	v_lshl_add_u64 v[120:121], s[38:39], 0, v[136:137]
	s_add_i32 m0, s40, 0x2000
	s_nop 0
	global_load_lds_dwordx4 v[120:121], off
	s_add_i32 s38, 0, 0x18000
	v_add_u32_e32 v146, s38, v151
	ds_read_b128 v[120:123], v146
	ds_read_b128 v[124:127], v146 offset:1024
	ds_read_b128 v[142:145], v146 offset:2048
	ds_read_b128 v[146:149], v146 offset:3072
	s_waitcnt vmcnt(6)
	s_barrier
	s_setprio 1
	v_mfma_f32_16x16x32_bf16 v[28:31], v[186:189], v[154:157], v[28:31]
	v_mfma_f32_16x16x32_bf16 v[24:27], v[204:207], v[154:157], v[24:27]
	v_mfma_f32_16x16x32_bf16 v[20:23], v[186:189], v[162:165], v[20:23]
	v_mfma_f32_16x16x32_bf16 v[16:19], v[204:207], v[162:165], v[16:19]
	v_mfma_f32_16x16x32_bf16 v[12:15], v[186:189], v[170:173], v[12:15]
	v_mfma_f32_16x16x32_bf16 v[8:11], v[204:207], v[170:173], v[8:11]
	v_mfma_f32_16x16x32_bf16 v[4:7], v[186:189], v[178:181], v[4:7]
	v_mfma_f32_16x16x32_bf16 v[0:3], v[204:207], v[178:181], v[0:3]
	v_mfma_f32_16x16x32_bf16 v[28:31], v[190:193], v[158:161], v[28:31]
	v_mfma_f32_16x16x32_bf16 v[24:27], v[208:211], v[158:161], v[24:27]
	v_mfma_f32_16x16x32_bf16 v[20:23], v[190:193], v[166:169], v[20:23]
	v_mfma_f32_16x16x32_bf16 v[16:19], v[208:211], v[166:169], v[16:19]
	v_mfma_f32_16x16x32_bf16 v[12:15], v[190:193], v[174:177], v[12:15]
	v_mfma_f32_16x16x32_bf16 v[8:11], v[208:211], v[174:177], v[8:11]
	v_mfma_f32_16x16x32_bf16 v[4:7], v[190:193], v[182:185], v[4:7]
	v_mfma_f32_16x16x32_bf16 v[0:3], v[208:211], v[182:185], v[0:3]
	s_setprio 0
	s_barrier
	s_add_u32 s12, s12, 0x40000
	s_addc_u32 s13, s13, 0
	s_mov_b32 m0, s22
	v_lshl_add_u64 v[186:187], s[12:13], 0, v[194:195]
	ds_read_b128 v[154:157], v153 offset:32768
	ds_read_b128 v[158:161], v153 offset:33792
	ds_read_b128 v[162:165], v153 offset:34816
	ds_read_b128 v[166:169], v153 offset:35840
	ds_read_b128 v[170:173], v153 offset:36864
	ds_read_b128 v[174:177], v153 offset:37888
	ds_read_b128 v[178:181], v153 offset:38912
	ds_read_b128 v[182:185], v153 offset:39936
	global_load_lds_dwordx4 v[186:187], off
	v_lshl_add_u64 v[186:187], s[12:13], 0, v[136:137]
	s_mov_b32 m0, s23
	s_nop 0
	global_load_lds_dwordx4 v[186:187], off
	s_waitcnt lgkmcnt(8)
	s_barrier
	s_waitcnt lgkmcnt(0)
	s_setprio 1
	s_waitcnt lgkmcnt(0)
	v_mfma_f32_16x16x32_bf16 v[132:135], v[120:123], v[154:157], v[132:135]
	v_mfma_f32_16x16x32_bf16 v[128:131], v[142:145], v[154:157], v[128:131]
	v_mfma_f32_16x16x32_bf16 v[116:119], v[120:123], v[162:165], v[116:119]
	v_mfma_f32_16x16x32_bf16 v[112:115], v[142:145], v[162:165], v[112:115]
	v_mfma_f32_16x16x32_bf16 v[108:111], v[120:123], v[170:173], v[108:111]
	v_mfma_f32_16x16x32_bf16 v[104:107], v[142:145], v[170:173], v[104:107]
	v_mfma_f32_16x16x32_bf16 v[100:103], v[120:123], v[178:181], v[100:103]
	v_mfma_f32_16x16x32_bf16 v[96:99], v[142:145], v[178:181], v[96:99]
	v_mfma_f32_16x16x32_bf16 v[132:135], v[124:127], v[158:161], v[132:135]
	v_mfma_f32_16x16x32_bf16 v[128:131], v[146:149], v[158:161], v[128:131]
	v_mfma_f32_16x16x32_bf16 v[116:119], v[124:127], v[166:169], v[116:119]
	v_mfma_f32_16x16x32_bf16 v[112:115], v[146:149], v[166:169], v[112:115]
	v_mfma_f32_16x16x32_bf16 v[108:111], v[124:127], v[174:177], v[108:111]
	v_mfma_f32_16x16x32_bf16 v[104:107], v[146:149], v[174:177], v[104:107]
	v_mfma_f32_16x16x32_bf16 v[100:103], v[124:127], v[182:185], v[100:103]
	v_mfma_f32_16x16x32_bf16 v[96:99], v[146:149], v[182:185], v[96:99]
	s_setprio 0
	s_barrier
	s_add_i32 s12, 0, 0x1c000
	s_add_i32 s13, s38, s19
	v_add_u32_e32 v208, s12, v151
	v_lshl_add_u64 v[212:213], v[212:213], 0, s[82:83]
	s_mov_b32 m0, s13
	ds_read_b128 v[186:189], v208
	ds_read_b128 v[190:193], v208 offset:1024
	ds_read_b128 v[204:207], v208 offset:2048
	ds_read_b128 v[208:211], v208 offset:3072
	global_load_lds_dwordx4 v[212:213], off
	v_lshl_add_u64 v[212:213], v[214:215], 0, s[82:83]
	s_add_i32 m0, s13, 0x2000
	s_nop 0
	global_load_lds_dwordx4 v[212:213], off
	s_barrier
	s_waitcnt lgkmcnt(0)
	s_setprio 1
	s_waitcnt lgkmcnt(0)
	v_mfma_f32_16x16x32_bf16 v[64:67], v[186:189], v[154:157], v[64:67]
	v_mfma_f32_16x16x32_bf16 v[56:59], v[204:207], v[154:157], v[56:59]
	v_mfma_f32_16x16x32_bf16 v[52:55], v[186:189], v[162:165], v[52:55]
	v_mfma_f32_16x16x32_bf16 v[48:51], v[204:207], v[162:165], v[48:51]
	v_mfma_f32_16x16x32_bf16 v[44:47], v[186:189], v[170:173], v[44:47]
	v_mfma_f32_16x16x32_bf16 v[40:43], v[204:207], v[170:173], v[40:43]
	v_mfma_f32_16x16x32_bf16 v[36:39], v[186:189], v[178:181], v[36:39]
	v_mfma_f32_16x16x32_bf16 v[32:35], v[204:207], v[178:181], v[32:35]
	v_mfma_f32_16x16x32_bf16 v[64:67], v[190:193], v[158:161], v[64:67]
	v_mfma_f32_16x16x32_bf16 v[56:59], v[208:211], v[158:161], v[56:59]
	v_mfma_f32_16x16x32_bf16 v[52:55], v[190:193], v[166:169], v[52:55]
	v_mfma_f32_16x16x32_bf16 v[48:51], v[208:211], v[166:169], v[48:51]
	v_mfma_f32_16x16x32_bf16 v[44:47], v[190:193], v[174:177], v[44:47]
	v_mfma_f32_16x16x32_bf16 v[40:43], v[208:211], v[174:177], v[40:43]
	v_mfma_f32_16x16x32_bf16 v[36:39], v[190:193], v[182:185], v[36:39]
	v_mfma_f32_16x16x32_bf16 v[32:35], v[208:211], v[182:185], v[32:35]
	s_setprio 0
	s_mov_b32 m0, s26
	v_lshl_add_u64 v[212:213], v[216:217], 0, s[82:83]
	s_barrier
	ds_read_b128 v[154:157], v153 offset:49152
	ds_read_b128 v[158:161], v153 offset:50176
	ds_read_b128 v[162:165], v153 offset:51200
	ds_read_b128 v[166:169], v153 offset:52224
	ds_read_b128 v[170:173], v153 offset:53248
	ds_read_b128 v[174:177], v153 offset:54272
	ds_read_b128 v[178:181], v153 offset:55296
	ds_read_b128 v[182:185], v153 offset:56320
	global_load_lds_dwordx4 v[212:213], off
	v_lshl_add_u64 v[212:213], v[236:237], 0, s[82:83]
	s_mov_b32 m0, s27
	s_nop 0
	global_load_lds_dwordx4 v[212:213], off
	s_barrier
	s_waitcnt lgkmcnt(0)
	s_setprio 1
	s_waitcnt lgkmcnt(0)
	v_mfma_f32_16x16x32_bf16 v[92:95], v[120:123], v[154:157], v[92:95]
	v_mfma_f32_16x16x32_bf16 v[88:91], v[142:145], v[154:157], v[88:91]
	v_mfma_f32_16x16x32_bf16 v[84:87], v[120:123], v[162:165], v[84:87]
	v_mfma_f32_16x16x32_bf16 v[80:83], v[142:145], v[162:165], v[80:83]
	v_mfma_f32_16x16x32_bf16 v[76:79], v[120:123], v[170:173], v[76:79]
	v_mfma_f32_16x16x32_bf16 v[72:75], v[142:145], v[170:173], v[72:75]
	v_mfma_f32_16x16x32_bf16 v[68:71], v[120:123], v[178:181], v[68:71]
	v_mfma_f32_16x16x32_bf16 v[60:63], v[142:145], v[178:181], v[60:63]
	v_mfma_f32_16x16x32_bf16 v[92:95], v[124:127], v[158:161], v[92:95]
	v_mfma_f32_16x16x32_bf16 v[88:91], v[146:149], v[158:161], v[88:91]
	v_mfma_f32_16x16x32_bf16 v[84:87], v[124:127], v[166:169], v[84:87]
	v_mfma_f32_16x16x32_bf16 v[80:83], v[146:149], v[166:169], v[80:83]
	v_mfma_f32_16x16x32_bf16 v[76:79], v[124:127], v[174:177], v[76:79]
	v_mfma_f32_16x16x32_bf16 v[72:75], v[146:149], v[174:177], v[72:75]
	v_mfma_f32_16x16x32_bf16 v[68:71], v[124:127], v[182:185], v[68:71]
	v_mfma_f32_16x16x32_bf16 v[60:63], v[146:149], v[182:185], v[60:63]
	s_setprio 0
	s_barrier
	s_add_u32 s10, s10, 0x40080
	s_addc_u32 s11, s11, 0
	s_add_i32 s12, s12, s19
	v_lshl_add_u64 v[120:121], s[10:11], 0, v[194:195]
	s_mov_b32 m0, s12
	s_nop 0
	global_load_lds_dwordx4 v[120:121], off
	v_lshl_add_u64 v[120:121], s[10:11], 0, v[136:137]
	s_add_i32 m0, s12, 0x2000
	s_nop 0
	global_load_lds_dwordx4 v[120:121], off
	s_waitcnt vmcnt(6)
	s_barrier
	s_setprio 1
	v_mfma_f32_16x16x32_bf16 v[28:31], v[186:189], v[154:157], v[28:31]
	v_mfma_f32_16x16x32_bf16 v[24:27], v[204:207], v[154:157], v[24:27]
	v_mfma_f32_16x16x32_bf16 v[20:23], v[186:189], v[162:165], v[20:23]
	v_mfma_f32_16x16x32_bf16 v[16:19], v[204:207], v[162:165], v[16:19]
	v_mfma_f32_16x16x32_bf16 v[12:15], v[186:189], v[170:173], v[12:15]
	v_mfma_f32_16x16x32_bf16 v[8:11], v[204:207], v[170:173], v[8:11]
	v_mfma_f32_16x16x32_bf16 v[4:7], v[186:189], v[178:181], v[4:7]
	v_mfma_f32_16x16x32_bf16 v[0:3], v[204:207], v[178:181], v[0:3]
	v_mfma_f32_16x16x32_bf16 v[28:31], v[190:193], v[158:161], v[28:31]
	v_mfma_f32_16x16x32_bf16 v[24:27], v[208:211], v[158:161], v[24:27]
	v_mfma_f32_16x16x32_bf16 v[20:23], v[190:193], v[166:169], v[20:23]
	v_mfma_f32_16x16x32_bf16 v[16:19], v[208:211], v[166:169], v[16:19]
	v_mfma_f32_16x16x32_bf16 v[12:15], v[190:193], v[174:177], v[12:15]
	v_mfma_f32_16x16x32_bf16 v[8:11], v[208:211], v[174:177], v[8:11]
	v_mfma_f32_16x16x32_bf16 v[4:7], v[190:193], v[182:185], v[4:7]
	v_mfma_f32_16x16x32_bf16 v[0:3], v[208:211], v[182:185], v[0:3]
	s_setprio 0
	s_add_i32 s37, s37, 2
	s_add_u32 s8, s8, 0x100
	s_addc_u32 s9, s9, 0
	s_add_u32 s35, s35, 0x100
	s_addc_u32 s36, s36, 0
	s_cmp_gt_u32 s37, 13
	s_barrier
	s_cbranch_scc0 .LBB0_766
	s_lshr_b32 s8, s31, 4
	s_mulk_i32 s8, 0xc00
	s_ashr_i32 s9, s8, 31
	v_lshl_or_b32 v120, s34, 8, v152
	s_lshl_b64 s[8:9], s[8:9], 2
	s_add_u32 s8, s24, s8
	v_ashrrev_i32_e32 v121, 31, v120
	v_lshl_add_u32 v148, s31, 8, v150
	s_addc_u32 s9, s25, s9
	v_lshlrev_b64 v[146:147], 2, v[120:121]
	v_lshl_add_u64 v[142:143], s[8:9], 0, v[146:147]
	v_ashrrev_i32_e32 v149, 31, v148
	v_readlane_b32 s8, v252, 25
	v_lshlrev_b64 v[162:163], 12, v[148:149]
	v_readlane_b32 s9, v252, 26
	global_load_dwordx4 v[120:123], v[142:143], off offset:16
	global_load_dwordx4 v[124:127], v[142:143], off
	v_lshl_add_u64 v[144:145], s[8:9], 0, v[162:163]
	v_lshl_add_u64 v[144:145], v[144:145], 0, v[146:147]
	global_load_dwordx4 v[154:157], v[144:145], off offset:16
	global_load_dwordx4 v[158:161], v[144:145], off
	s_and_b64 vcc, exec, s[4:5]
	s_mov_b32 s31, s30
	s_mov_b32 s34, s29
	s_mov_b64 s[10:11], s[6:7]
	s_waitcnt vmcnt(0)
	v_pk_fma_f32 v[130:131], v[130:131], v[122:123], v[156:157]
	v_pk_fma_f32 v[158:159], v[132:133], v[124:125], v[158:159]
	v_lshl_add_u64 v[132:133], s[94:95], 0, v[162:163]
	v_lshl_add_u64 v[132:133], v[132:133], 0, v[146:147]
	v_pk_fma_f32 v[128:129], v[128:129], v[120:121], v[154:155]
	global_store_dwordx4 v[132:133], v[128:131], off offset:16
	v_pk_fma_f32 v[160:161], v[134:135], v[126:127], v[160:161]
	global_store_dwordx4 v[132:133], v[158:161], off
	v_or_b32_e32 v128, 16, v148
	v_ashrrev_i32_e32 v129, 31, v128
	v_lshlrev_b64 v[130:131], 12, v[128:129]
	v_lshl_add_u64 v[128:129], s[8:9], 0, v[130:131]
	v_lshl_add_u64 v[128:129], v[128:129], 0, v[146:147]
	global_load_dwordx4 v[154:157], v[128:129], off offset:16
	global_load_dwordx4 v[158:161], v[128:129], off
	s_waitcnt vmcnt(0)
	v_pk_fma_f32 v[114:115], v[114:115], v[122:123], v[156:157]
	v_pk_fma_f32 v[158:159], v[116:117], v[124:125], v[158:159]
	v_lshl_add_u64 v[116:117], s[94:95], 0, v[130:131]
	v_lshl_add_u64 v[116:117], v[116:117], 0, v[146:147]
	v_pk_fma_f32 v[112:113], v[112:113], v[120:121], v[154:155]
	global_store_dwordx4 v[116:117], v[112:115], off offset:16
	v_pk_fma_f32 v[160:161], v[118:119], v[126:127], v[160:161]
	global_store_dwordx4 v[116:117], v[158:161], off
	v_or_b32_e32 v112, 32, v148
	v_ashrrev_i32_e32 v113, 31, v112
	v_lshlrev_b64 v[114:115], 12, v[112:113]
	v_lshl_add_u64 v[112:113], s[8:9], 0, v[114:115]
	v_lshl_add_u64 v[112:113], v[112:113], 0, v[146:147]
	global_load_dwordx4 v[154:157], v[112:113], off offset:16
	global_load_dwordx4 v[158:161], v[112:113], off
	s_waitcnt vmcnt(0)
	v_pk_fma_f32 v[106:107], v[106:107], v[122:123], v[156:157]
	v_pk_fma_f32 v[158:159], v[108:109], v[124:125], v[158:159]
	v_lshl_add_u64 v[108:109], s[94:95], 0, v[114:115]
	v_lshl_add_u64 v[108:109], v[108:109], 0, v[146:147]
	v_pk_fma_f32 v[104:105], v[104:105], v[120:121], v[154:155]
	global_store_dwordx4 v[108:109], v[104:107], off offset:16
	v_pk_fma_f32 v[160:161], v[110:111], v[126:127], v[160:161]
	global_store_dwordx4 v[108:109], v[158:161], off
	v_or_b32_e32 v104, 48, v148
	v_ashrrev_i32_e32 v105, 31, v104
	v_lshlrev_b64 v[106:107], 12, v[104:105]
	v_lshl_add_u64 v[104:105], s[8:9], 0, v[106:107]
	v_lshl_add_u64 v[104:105], v[104:105], 0, v[146:147]
	global_load_dwordx4 v[154:157], v[104:105], off offset:16
	global_load_dwordx4 v[158:161], v[104:105], off
	s_waitcnt vmcnt(0)
	v_pk_fma_f32 v[98:99], v[98:99], v[122:123], v[156:157]
	v_pk_fma_f32 v[158:159], v[100:101], v[124:125], v[158:159]
	v_lshl_add_u64 v[100:101], s[94:95], 0, v[106:107]
	v_lshl_add_u64 v[100:101], v[100:101], 0, v[146:147]
	v_pk_fma_f32 v[96:97], v[96:97], v[120:121], v[154:155]
	global_store_dwordx4 v[100:101], v[96:99], off offset:16
	v_pk_fma_f32 v[160:161], v[102:103], v[126:127], v[160:161]
	global_store_dwordx4 v[100:101], v[158:161], off
	v_add_u32_e32 v96, 0x80, v148
	v_ashrrev_i32_e32 v97, 31, v96
	v_lshlrev_b64 v[98:99], 12, v[96:97]
	v_lshl_add_u64 v[96:97], s[8:9], 0, v[98:99]
	v_lshl_add_u64 v[96:97], v[96:97], 0, v[146:147]
	global_load_dwordx4 v[154:157], v[96:97], off offset:16
	global_load_dwordx4 v[158:161], v[96:97], off
	s_waitcnt vmcnt(0)
	v_pk_fma_f32 v[90:91], v[90:91], v[122:123], v[156:157]
	v_pk_fma_f32 v[158:159], v[92:93], v[124:125], v[158:159]
	v_lshl_add_u64 v[92:93], s[94:95], 0, v[98:99]
	v_lshl_add_u64 v[92:93], v[92:93], 0, v[146:147]
	v_pk_fma_f32 v[88:89], v[88:89], v[120:121], v[154:155]
	global_store_dwordx4 v[92:93], v[88:91], off offset:16
	v_pk_fma_f32 v[160:161], v[94:95], v[126:127], v[160:161]
	global_store_dwordx4 v[92:93], v[158:161], off
	v_add_u32_e32 v88, 0x90, v148
	v_ashrrev_i32_e32 v89, 31, v88
	v_lshlrev_b64 v[90:91], 12, v[88:89]
	v_lshl_add_u64 v[88:89], s[8:9], 0, v[90:91]
	v_lshl_add_u64 v[88:89], v[88:89], 0, v[146:147]
	global_load_dwordx4 v[154:157], v[88:89], off offset:16
	global_load_dwordx4 v[158:161], v[88:89], off
	s_waitcnt vmcnt(0)
	v_pk_fma_f32 v[82:83], v[82:83], v[122:123], v[156:157]
	v_pk_fma_f32 v[158:159], v[84:85], v[124:125], v[158:159]
	v_lshl_add_u64 v[84:85], s[94:95], 0, v[90:91]
	v_lshl_add_u64 v[84:85], v[84:85], 0, v[146:147]
	v_pk_fma_f32 v[80:81], v[80:81], v[120:121], v[154:155]
	global_store_dwordx4 v[84:85], v[80:83], off offset:16
	v_pk_fma_f32 v[160:161], v[86:87], v[126:127], v[160:161]
	global_store_dwordx4 v[84:85], v[158:161], off
	v_add_u32_e32 v80, 0xa0, v148
	v_ashrrev_i32_e32 v81, 31, v80
	v_lshlrev_b64 v[82:83], 12, v[80:81]
	v_lshl_add_u64 v[80:81], s[8:9], 0, v[82:83]
	v_lshl_add_u64 v[80:81], v[80:81], 0, v[146:147]
	global_load_dwordx4 v[154:157], v[80:81], off offset:16
	global_load_dwordx4 v[158:161], v[80:81], off
	s_waitcnt vmcnt(0)
	v_pk_fma_f32 v[74:75], v[74:75], v[122:123], v[156:157]
	v_pk_fma_f32 v[158:159], v[76:77], v[124:125], v[158:159]
	v_lshl_add_u64 v[76:77], s[94:95], 0, v[82:83]
	v_lshl_add_u64 v[76:77], v[76:77], 0, v[146:147]
	v_pk_fma_f32 v[72:73], v[72:73], v[120:121], v[154:155]
	global_store_dwordx4 v[76:77], v[72:75], off offset:16
	v_pk_fma_f32 v[160:161], v[78:79], v[126:127], v[160:161]
	global_store_dwordx4 v[76:77], v[158:161], off
	v_add_u32_e32 v72, 0xb0, v148
	v_ashrrev_i32_e32 v73, 31, v72
	v_lshlrev_b64 v[74:75], 12, v[72:73]
	v_lshl_add_u64 v[72:73], s[8:9], 0, v[74:75]
	v_lshl_add_u64 v[72:73], v[72:73], 0, v[146:147]
	global_load_dwordx4 v[154:157], v[72:73], off offset:16
	global_load_dwordx4 v[158:161], v[72:73], off
	v_lshl_add_u64 v[74:75], s[94:95], 0, v[74:75]
	v_lshl_add_u64 v[74:75], v[74:75], 0, v[146:147]
	s_mov_b64 s[8:9], s[0:1]
	s_waitcnt vmcnt(0)
	v_pk_fma_f32 v[62:63], v[62:63], v[122:123], v[156:157]
	v_pk_fma_f32 v[70:71], v[70:71], v[126:127], v[160:161]
	v_pk_fma_f32 v[68:69], v[68:69], v[124:125], v[158:159]
	v_pk_fma_f32 v[60:61], v[60:61], v[120:121], v[154:155]
	global_store_dwordx4 v[74:75], v[68:71], off
	global_store_dwordx4 v[74:75], v[60:63], off offset:16
	global_load_dwordx4 v[60:63], v[142:143], off offset:528
	s_nop 0
	global_load_dwordx4 v[68:71], v[142:143], off offset:512
	global_load_dwordx4 v[118:121], v[144:145], off offset:528
	global_load_dwordx4 v[122:125], v[144:145], off offset:512
	s_waitcnt vmcnt(0)
	v_pk_fma_f32 v[58:59], v[58:59], v[62:63], v[120:121]
	v_pk_fma_f32 v[66:67], v[66:67], v[70:71], v[124:125]
	v_pk_fma_f32 v[64:65], v[64:65], v[68:69], v[122:123]
	v_pk_fma_f32 v[56:57], v[56:57], v[60:61], v[118:119]
	global_store_dwordx4 v[132:133], v[64:67], off offset:512
	global_store_dwordx4 v[132:133], v[56:59], off offset:528
	global_load_dwordx4 v[56:59], v[128:129], off offset:528
	s_nop 0
	global_load_dwordx4 v[64:67], v[128:129], off offset:512
	s_waitcnt vmcnt(0)
	v_pk_fma_f32 v[50:51], v[50:51], v[62:63], v[58:59]
	v_pk_fma_f32 v[54:55], v[54:55], v[70:71], v[66:67]
	v_pk_fma_f32 v[52:53], v[52:53], v[68:69], v[64:65]
	v_pk_fma_f32 v[48:49], v[48:49], v[60:61], v[56:57]
	global_store_dwordx4 v[116:117], v[52:55], off offset:512
	global_store_dwordx4 v[116:117], v[48:51], off offset:528
	global_load_dwordx4 v[48:51], v[112:113], off offset:528
	s_nop 0
	global_load_dwordx4 v[52:55], v[112:113], off offset:512
	s_waitcnt vmcnt(0)
	v_pk_fma_f32 v[42:43], v[42:43], v[62:63], v[50:51]
	v_pk_fma_f32 v[46:47], v[46:47], v[70:71], v[54:55]
	v_pk_fma_f32 v[44:45], v[44:45], v[68:69], v[52:53]
	v_pk_fma_f32 v[40:41], v[40:41], v[60:61], v[48:49]
	global_store_dwordx4 v[108:109], v[44:47], off offset:512
	global_store_dwordx4 v[108:109], v[40:43], off offset:528
	global_load_dwordx4 v[40:43], v[104:105], off offset:528
	s_nop 0
	global_load_dwordx4 v[44:47], v[104:105], off offset:512
	s_waitcnt vmcnt(0)
	v_pk_fma_f32 v[34:35], v[34:35], v[62:63], v[42:43]
	v_pk_fma_f32 v[38:39], v[38:39], v[70:71], v[46:47]
	v_pk_fma_f32 v[36:37], v[36:37], v[68:69], v[44:45]
	v_pk_fma_f32 v[32:33], v[32:33], v[60:61], v[40:41]
	global_store_dwordx4 v[100:101], v[36:39], off offset:512
	global_store_dwordx4 v[100:101], v[32:35], off offset:528
	global_load_dwordx4 v[32:35], v[96:97], off offset:528
	s_nop 0
	global_load_dwordx4 v[36:39], v[96:97], off offset:512
	s_waitcnt vmcnt(0)
	v_pk_fma_f32 v[26:27], v[26:27], v[62:63], v[34:35]
	v_pk_fma_f32 v[30:31], v[30:31], v[70:71], v[38:39]
	v_pk_fma_f32 v[28:29], v[28:29], v[68:69], v[36:37]
	v_pk_fma_f32 v[24:25], v[24:25], v[60:61], v[32:33]
	global_store_dwordx4 v[92:93], v[28:31], off offset:512
	global_store_dwordx4 v[92:93], v[24:27], off offset:528
	global_load_dwordx4 v[24:27], v[88:89], off offset:528
	s_nop 0
	global_load_dwordx4 v[28:31], v[88:89], off offset:512
	s_waitcnt vmcnt(0)
	v_pk_fma_f32 v[18:19], v[18:19], v[62:63], v[26:27]
	v_pk_fma_f32 v[22:23], v[22:23], v[70:71], v[30:31]
	v_pk_fma_f32 v[20:21], v[20:21], v[68:69], v[28:29]
	v_pk_fma_f32 v[16:17], v[16:17], v[60:61], v[24:25]
	global_store_dwordx4 v[84:85], v[20:23], off offset:512
	global_store_dwordx4 v[84:85], v[16:19], off offset:528
	global_load_dwordx4 v[16:19], v[80:81], off offset:528
	s_nop 0
	global_load_dwordx4 v[20:23], v[80:81], off offset:512
	s_waitcnt vmcnt(0)
	v_pk_fma_f32 v[10:11], v[10:11], v[62:63], v[18:19]
	v_pk_fma_f32 v[14:15], v[14:15], v[70:71], v[22:23]
	v_pk_fma_f32 v[12:13], v[12:13], v[68:69], v[20:21]
	v_pk_fma_f32 v[8:9], v[8:9], v[60:61], v[16:17]
	global_store_dwordx4 v[76:77], v[12:15], off offset:512
	global_store_dwordx4 v[76:77], v[8:11], off offset:528
	global_load_dwordx4 v[8:11], v[72:73], off offset:528
	s_nop 0
	global_load_dwordx4 v[12:15], v[72:73], off offset:512
	s_waitcnt vmcnt(0)
	v_pk_fma_f32 v[2:3], v[2:3], v[62:63], v[10:11]
	v_pk_fma_f32 v[6:7], v[6:7], v[70:71], v[14:15]
	v_pk_fma_f32 v[4:5], v[4:5], v[68:69], v[12:13]
	v_pk_fma_f32 v[0:1], v[0:1], v[60:61], v[8:9]
	global_store_dwordx4 v[74:75], v[4:7], off offset:512
	global_store_dwordx4 v[74:75], v[0:3], off offset:528
	s_cbranch_vccz .LBB0_763
	s_waitcnt vmcnt(0)
	s_cmpk_gt_u32 s14, 0xff
	s_cbranch_scc1 .LBB0_770
	s_barrier
